# RWKV scan consumer: r operands rotate over three register sets so all six LDS reads of a step go out as one burst; interleaved chunk-tail reductions
# baseline (speedup 1.0000x reference)
.LBB0_1750:
	s_and_b32 s23, s22, 1
	s_mul_i32 s2, s23, 0xc000
	s_add_i32 s2, s2, 0
	v_add_u32_e32 v20, s2, v10
	s_add_i32 s2, s2, s5
	v_lshl_add_u32 v21, v1, 2, s2
	ds_read_b128 v[36:39], v20 offset:0
	ds_read_b128 v[40:43], v20 offset:8192
	ds_read_b64 v[56:57], v21 offset:40960
	ds_read_b128 v[48:51], v20 offset:24576
	ds_read_b128 v[44:47], v20 offset:16384
	ds_read_b128 v[52:55], v20 offset:32768
	s_waitcnt lgkmcnt(0)
	ds_read_b128 v[60:63], v20 offset:256
	ds_read_b128 v[64:67], v20 offset:8448
	ds_read_b64 v[80:81], v21 offset:41216
	ds_read_b128 v[72:75], v20 offset:24832
	ds_read_b128 v[68:71], v20 offset:16640
	ds_read_b128 v[76:79], v20 offset:33024
	v_pk_mul_f32 v[22:23], v[2:3], v[36:37] op_sel:[0,0] op_sel_hi:[1,0]
	v_pk_fma_f32 v[22:23], v[4:5], v[36:37], v[22:23] op_sel:[0,1,0] op_sel_hi:[1,1,1]
	v_pk_fma_f32 v[22:23], v[6:7], v[38:39], v[22:23] op_sel:[0,0,0] op_sel_hi:[1,0,1]
	v_pk_fma_f32 v[22:23], v[8:9], v[38:39], v[22:23] op_sel:[0,1,0] op_sel_hi:[1,1,1]
	s_nop 1
	v_add_f32_dpp v22, v22, v22 quad_perm:[1,0,3,2] row_mask:0xf bank_mask:0xf
	v_add_f32_dpp v23, v23, v23 quad_perm:[1,0,3,2] row_mask:0xf bank_mask:0xf
	v_pk_mul_f32 v[84:85], v[2:3], v[40:41] op_sel:[0,0] op_sel_hi:[1,0]
	v_pk_mul_f32 v[86:87], v[4:5], v[40:41] op_sel:[0,1] op_sel_hi:[1,1]
	v_add_f32_dpp v22, v22, v22 quad_perm:[2,3,0,1] row_mask:0xf bank_mask:0xf
	v_add_f32_dpp v23, v23, v23 quad_perm:[2,3,0,1] row_mask:0xf bank_mask:0xf
	v_pk_mul_f32 v[88:89], v[6:7], v[42:43] op_sel:[0,0] op_sel_hi:[1,0]
	v_pk_mul_f32 v[90:91], v[8:9], v[42:43] op_sel:[0,1] op_sel_hi:[1,1]
	v_add_f32_dpp v22, v22, v22 row_half_mirror row_mask:0xf bank_mask:0xf
	v_add_f32_dpp v23, v23, v23 row_half_mirror row_mask:0xf bank_mask:0xf
	v_pk_fma_f32 v[84:85], v[48:49], v[56:57], v[84:85] op_sel:[0,0,0] op_sel_hi:[0,1,1]
	v_pk_fma_f32 v[86:87], v[48:49], v[56:57], v[86:87] op_sel:[1,0,0] op_sel_hi:[1,1,1]
	v_add_f32_dpp v22, v22, v22 row_mirror row_mask:0xf bank_mask:0xf
	v_add_f32_dpp v23, v23, v23 row_mirror row_mask:0xf bank_mask:0xf
	v_pk_fma_f32 v[88:89], v[50:51], v[56:57], v[88:89] op_sel:[0,0,0] op_sel_hi:[0,1,1]
	v_pk_fma_f32 v[90:91], v[50:51], v[56:57], v[90:91] op_sel:[1,0,0] op_sel_hi:[1,1,1]
	v_pk_fma_f32 v[2:3], v[44:45], v[22:23], v[84:85] op_sel:[0,0,0] op_sel_hi:[0,1,1] neg_lo:[1,0,0] neg_hi:[1,0,0]
	v_pk_fma_f32 v[4:5], v[44:45], v[22:23], v[86:87] op_sel:[1,0,0] op_sel_hi:[1,1,1] neg_lo:[1,0,0] neg_hi:[1,0,0]
	v_pk_fma_f32 v[6:7], v[46:47], v[22:23], v[88:89] op_sel:[0,0,0] op_sel_hi:[0,1,1] neg_lo:[1,0,0] neg_hi:[1,0,0]
	v_pk_fma_f32 v[8:9], v[46:47], v[22:23], v[90:91] op_sel:[1,0,0] op_sel_hi:[1,1,1] neg_lo:[1,0,0] neg_hi:[1,0,0]
	s_waitcnt lgkmcnt(0)
	ds_read_b128 v[36:39], v20 offset:512
	ds_read_b128 v[40:43], v20 offset:8704
	ds_read_b64 v[56:57], v21 offset:41472
	ds_read_b128 v[48:51], v20 offset:25088
	ds_read_b128 v[44:47], v20 offset:16896
	ds_read_b128 v[92:95], v20 offset:33280
	v_pk_mul_f32 v[22:23], v[2:3], v[60:61] op_sel:[0,0] op_sel_hi:[1,0]
	v_pk_mul_f32 v[24:25], v[2:3], v[52:53] op_sel:[0,0] op_sel_hi:[1,0]
	v_pk_fma_f32 v[22:23], v[4:5], v[60:61], v[22:23] op_sel:[0,1,0] op_sel_hi:[1,1,1]
	v_pk_fma_f32 v[24:25], v[4:5], v[52:53], v[24:25] op_sel:[0,1,0] op_sel_hi:[1,1,1]
	v_pk_fma_f32 v[22:23], v[6:7], v[62:63], v[22:23] op_sel:[0,0,0] op_sel_hi:[1,0,1]
	v_pk_fma_f32 v[24:25], v[6:7], v[54:55], v[24:25] op_sel:[0,0,0] op_sel_hi:[1,0,1]
	v_pk_fma_f32 v[22:23], v[8:9], v[62:63], v[22:23] op_sel:[0,1,0] op_sel_hi:[1,1,1]
	v_pk_fma_f32 v[24:25], v[8:9], v[54:55], v[24:25] op_sel:[0,1,0] op_sel_hi:[1,1,1]
	s_nop 0
	v_add_f32_dpp v22, v22, v22 quad_perm:[1,0,3,2] row_mask:0xf bank_mask:0xf
	v_add_f32_dpp v23, v23, v23 quad_perm:[1,0,3,2] row_mask:0xf bank_mask:0xf
	v_pk_mul_f32 v[84:85], v[2:3], v[64:65] op_sel:[0,0] op_sel_hi:[1,0]
	v_pk_mul_f32 v[86:87], v[4:5], v[64:65] op_sel:[0,1] op_sel_hi:[1,1]
	v_add_f32_dpp v22, v22, v22 quad_perm:[2,3,0,1] row_mask:0xf bank_mask:0xf
	v_add_f32_dpp v23, v23, v23 quad_perm:[2,3,0,1] row_mask:0xf bank_mask:0xf
	v_pk_mul_f32 v[88:89], v[6:7], v[66:67] op_sel:[0,0] op_sel_hi:[1,0]
	v_pk_mul_f32 v[90:91], v[8:9], v[66:67] op_sel:[0,1] op_sel_hi:[1,1]
	v_add_f32_dpp v22, v22, v22 row_half_mirror row_mask:0xf bank_mask:0xf
	v_add_f32_dpp v23, v23, v23 row_half_mirror row_mask:0xf bank_mask:0xf
	v_pk_fma_f32 v[84:85], v[72:73], v[80:81], v[84:85] op_sel:[0,0,0] op_sel_hi:[0,1,1]
	v_pk_fma_f32 v[86:87], v[72:73], v[80:81], v[86:87] op_sel:[1,0,0] op_sel_hi:[1,1,1]
	v_add_f32_dpp v22, v22, v22 row_mirror row_mask:0xf bank_mask:0xf
	v_add_f32_dpp v23, v23, v23 row_mirror row_mask:0xf bank_mask:0xf
	v_pk_fma_f32 v[88:89], v[74:75], v[80:81], v[88:89] op_sel:[0,0,0] op_sel_hi:[0,1,1]
	v_pk_fma_f32 v[90:91], v[74:75], v[80:81], v[90:91] op_sel:[1,0,0] op_sel_hi:[1,1,1]
	v_pk_fma_f32 v[2:3], v[68:69], v[22:23], v[84:85] op_sel:[0,0,0] op_sel_hi:[0,1,1] neg_lo:[1,0,0] neg_hi:[1,0,0]
	v_pk_fma_f32 v[4:5], v[68:69], v[22:23], v[86:87] op_sel:[1,0,0] op_sel_hi:[1,1,1] neg_lo:[1,0,0] neg_hi:[1,0,0]
	v_pk_fma_f32 v[6:7], v[70:71], v[22:23], v[88:89] op_sel:[0,0,0] op_sel_hi:[0,1,1] neg_lo:[1,0,0] neg_hi:[1,0,0]
	v_pk_fma_f32 v[8:9], v[70:71], v[22:23], v[90:91] op_sel:[1,0,0] op_sel_hi:[1,1,1] neg_lo:[1,0,0] neg_hi:[1,0,0]
	s_waitcnt lgkmcnt(0)
	ds_read_b128 v[60:63], v20 offset:768
	ds_read_b128 v[64:67], v20 offset:8960
	ds_read_b64 v[80:81], v21 offset:41728
	ds_read_b128 v[72:75], v20 offset:25344
	ds_read_b128 v[68:71], v20 offset:17152
	ds_read_b128 v[52:55], v20 offset:33536
	v_pk_mul_f32 v[22:23], v[2:3], v[36:37] op_sel:[0,0] op_sel_hi:[1,0]
	v_pk_mul_f32 v[26:27], v[2:3], v[76:77] op_sel:[0,0] op_sel_hi:[1,0]
	v_pk_fma_f32 v[22:23], v[4:5], v[36:37], v[22:23] op_sel:[0,1,0] op_sel_hi:[1,1,1]
	v_pk_fma_f32 v[26:27], v[4:5], v[76:77], v[26:27] op_sel:[0,1,0] op_sel_hi:[1,1,1]
	v_pk_fma_f32 v[22:23], v[6:7], v[38:39], v[22:23] op_sel:[0,0,0] op_sel_hi:[1,0,1]
	v_pk_fma_f32 v[26:27], v[6:7], v[78:79], v[26:27] op_sel:[0,0,0] op_sel_hi:[1,0,1]
	v_pk_fma_f32 v[22:23], v[8:9], v[38:39], v[22:23] op_sel:[0,1,0] op_sel_hi:[1,1,1]
	v_pk_fma_f32 v[26:27], v[8:9], v[78:79], v[26:27] op_sel:[0,1,0] op_sel_hi:[1,1,1]
	s_nop 0
	v_add_f32_dpp v22, v22, v22 quad_perm:[1,0,3,2] row_mask:0xf bank_mask:0xf
	v_add_f32_dpp v23, v23, v23 quad_perm:[1,0,3,2] row_mask:0xf bank_mask:0xf
	v_pk_mul_f32 v[84:85], v[2:3], v[40:41] op_sel:[0,0] op_sel_hi:[1,0]
	v_pk_mul_f32 v[86:87], v[4:5], v[40:41] op_sel:[0,1] op_sel_hi:[1,1]
	v_add_f32_dpp v22, v22, v22 quad_perm:[2,3,0,1] row_mask:0xf bank_mask:0xf
	v_add_f32_dpp v23, v23, v23 quad_perm:[2,3,0,1] row_mask:0xf bank_mask:0xf
	v_pk_mul_f32 v[88:89], v[6:7], v[42:43] op_sel:[0,0] op_sel_hi:[1,0]
	v_pk_mul_f32 v[90:91], v[8:9], v[42:43] op_sel:[0,1] op_sel_hi:[1,1]
	v_add_f32_dpp v22, v22, v22 row_half_mirror row_mask:0xf bank_mask:0xf
	v_add_f32_dpp v23, v23, v23 row_half_mirror row_mask:0xf bank_mask:0xf
	v_pk_fma_f32 v[84:85], v[48:49], v[56:57], v[84:85] op_sel:[0,0,0] op_sel_hi:[0,1,1]
	v_pk_fma_f32 v[86:87], v[48:49], v[56:57], v[86:87] op_sel:[1,0,0] op_sel_hi:[1,1,1]
	v_add_f32_dpp v22, v22, v22 row_mirror row_mask:0xf bank_mask:0xf
	v_add_f32_dpp v23, v23, v23 row_mirror row_mask:0xf bank_mask:0xf
	v_pk_fma_f32 v[88:89], v[50:51], v[56:57], v[88:89] op_sel:[0,0,0] op_sel_hi:[0,1,1]
	v_pk_fma_f32 v[90:91], v[50:51], v[56:57], v[90:91] op_sel:[1,0,0] op_sel_hi:[1,1,1]
	v_pk_fma_f32 v[2:3], v[44:45], v[22:23], v[84:85] op_sel:[0,0,0] op_sel_hi:[0,1,1] neg_lo:[1,0,0] neg_hi:[1,0,0]
	v_pk_fma_f32 v[4:5], v[44:45], v[22:23], v[86:87] op_sel:[1,0,0] op_sel_hi:[1,1,1] neg_lo:[1,0,0] neg_hi:[1,0,0]
	v_pk_fma_f32 v[6:7], v[46:47], v[22:23], v[88:89] op_sel:[0,0,0] op_sel_hi:[0,1,1] neg_lo:[1,0,0] neg_hi:[1,0,0]
	v_pk_fma_f32 v[8:9], v[46:47], v[22:23], v[90:91] op_sel:[1,0,0] op_sel_hi:[1,1,1] neg_lo:[1,0,0] neg_hi:[1,0,0]
	s_waitcnt lgkmcnt(0)
	ds_read_b128 v[36:39], v20 offset:1024
	ds_read_b128 v[40:43], v20 offset:9216
	ds_read_b64 v[56:57], v21 offset:41984
	ds_read_b128 v[48:51], v20 offset:25600
	ds_read_b128 v[44:47], v20 offset:17408
	ds_read_b128 v[76:79], v20 offset:33792
	v_pk_mul_f32 v[22:23], v[2:3], v[60:61] op_sel:[0,0] op_sel_hi:[1,0]
	v_pk_mul_f32 v[28:29], v[2:3], v[92:93] op_sel:[0,0] op_sel_hi:[1,0]
	v_pk_fma_f32 v[22:23], v[4:5], v[60:61], v[22:23] op_sel:[0,1,0] op_sel_hi:[1,1,1]
	v_pk_fma_f32 v[28:29], v[4:5], v[92:93], v[28:29] op_sel:[0,1,0] op_sel_hi:[1,1,1]
	v_pk_fma_f32 v[22:23], v[6:7], v[62:63], v[22:23] op_sel:[0,0,0] op_sel_hi:[1,0,1]
	v_pk_fma_f32 v[28:29], v[6:7], v[94:95], v[28:29] op_sel:[0,0,0] op_sel_hi:[1,0,1]
	v_pk_fma_f32 v[22:23], v[8:9], v[62:63], v[22:23] op_sel:[0,1,0] op_sel_hi:[1,1,1]
	v_pk_fma_f32 v[28:29], v[8:9], v[94:95], v[28:29] op_sel:[0,1,0] op_sel_hi:[1,1,1]
	v_add_f32_dpp v24, v24, v24 row_ror:12 row_mask:0xf bank_mask:0x5
	v_add_f32_dpp v25, v25, v25 row_ror:4 row_mask:0xf bank_mask:0xa
	v_add_f32_dpp v22, v22, v22 quad_perm:[1,0,3,2] row_mask:0xf bank_mask:0xf
	v_add_f32_dpp v23, v23, v23 quad_perm:[1,0,3,2] row_mask:0xf bank_mask:0xf
	v_pk_mul_f32 v[84:85], v[2:3], v[64:65] op_sel:[0,0] op_sel_hi:[1,0]
	v_pk_mul_f32 v[86:87], v[4:5], v[64:65] op_sel:[0,1] op_sel_hi:[1,1]
	v_add_f32_dpp v26, v26, v26 row_ror:12 row_mask:0xf bank_mask:0x5
	v_add_f32_dpp v22, v22, v22 quad_perm:[2,3,0,1] row_mask:0xf bank_mask:0xf
	v_add_f32_dpp v23, v23, v23 quad_perm:[2,3,0,1] row_mask:0xf bank_mask:0xf
	v_pk_mul_f32 v[88:89], v[6:7], v[66:67] op_sel:[0,0] op_sel_hi:[1,0]
	v_pk_mul_f32 v[90:91], v[8:9], v[66:67] op_sel:[0,1] op_sel_hi:[1,1]
	v_add_f32_dpp v27, v27, v27 row_ror:4 row_mask:0xf bank_mask:0xa
	v_add_f32_dpp v22, v22, v22 row_half_mirror row_mask:0xf bank_mask:0xf
	v_add_f32_dpp v23, v23, v23 row_half_mirror row_mask:0xf bank_mask:0xf
	v_pk_fma_f32 v[84:85], v[72:73], v[80:81], v[84:85] op_sel:[0,0,0] op_sel_hi:[0,1,1]
	v_pk_fma_f32 v[86:87], v[72:73], v[80:81], v[86:87] op_sel:[1,0,0] op_sel_hi:[1,1,1]
	v_mov_b32_dpp v24, v25 quad_perm:[0,1,2,3] row_mask:0xf bank_mask:0xa
	v_add_f32_dpp v22, v22, v22 row_mirror row_mask:0xf bank_mask:0xf
	v_add_f32_dpp v23, v23, v23 row_mirror row_mask:0xf bank_mask:0xf
	v_pk_fma_f32 v[88:89], v[74:75], v[80:81], v[88:89] op_sel:[0,0,0] op_sel_hi:[0,1,1]
	v_pk_fma_f32 v[90:91], v[74:75], v[80:81], v[90:91] op_sel:[1,0,0] op_sel_hi:[1,1,1]
	v_mov_b32_dpp v26, v27 quad_perm:[0,1,2,3] row_mask:0xf bank_mask:0xa
	v_pk_fma_f32 v[2:3], v[68:69], v[22:23], v[84:85] op_sel:[0,0,0] op_sel_hi:[0,1,1] neg_lo:[1,0,0] neg_hi:[1,0,0]
	v_pk_fma_f32 v[4:5], v[68:69], v[22:23], v[86:87] op_sel:[1,0,0] op_sel_hi:[1,1,1] neg_lo:[1,0,0] neg_hi:[1,0,0]
	v_pk_fma_f32 v[6:7], v[70:71], v[22:23], v[88:89] op_sel:[0,0,0] op_sel_hi:[0,1,1] neg_lo:[1,0,0] neg_hi:[1,0,0]
	v_pk_fma_f32 v[8:9], v[70:71], v[22:23], v[90:91] op_sel:[1,0,0] op_sel_hi:[1,1,1] neg_lo:[1,0,0] neg_hi:[1,0,0]
	s_waitcnt lgkmcnt(0)
	ds_read_b128 v[60:63], v20 offset:1280
	ds_read_b128 v[64:67], v20 offset:9472
	ds_read_b64 v[80:81], v21 offset:42240
	ds_read_b128 v[72:75], v20 offset:25856
	ds_read_b128 v[68:71], v20 offset:17664
	ds_read_b128 v[92:95], v20 offset:34048
	v_pk_mul_f32 v[22:23], v[2:3], v[36:37] op_sel:[0,0] op_sel_hi:[1,0]
	v_pk_mul_f32 v[58:59], v[2:3], v[52:53] op_sel:[0,0] op_sel_hi:[1,0]
	v_pk_fma_f32 v[22:23], v[4:5], v[36:37], v[22:23] op_sel:[0,1,0] op_sel_hi:[1,1,1]
	v_pk_fma_f32 v[58:59], v[4:5], v[52:53], v[58:59] op_sel:[0,1,0] op_sel_hi:[1,1,1]
	v_pk_fma_f32 v[22:23], v[6:7], v[38:39], v[22:23] op_sel:[0,0,0] op_sel_hi:[1,0,1]
	v_pk_fma_f32 v[58:59], v[6:7], v[54:55], v[58:59] op_sel:[0,0,0] op_sel_hi:[1,0,1]
	v_pk_fma_f32 v[22:23], v[8:9], v[38:39], v[22:23] op_sel:[0,1,0] op_sel_hi:[1,1,1]
	v_pk_fma_f32 v[58:59], v[8:9], v[54:55], v[58:59] op_sel:[0,1,0] op_sel_hi:[1,1,1]
	v_add_f32_dpp v24, v24, v24 row_ror:8 row_mask:0xf bank_mask:0x3
	v_add_f32_dpp v26, v26, v26 row_ror:8 row_mask:0xf bank_mask:0xc
	v_add_f32_dpp v22, v22, v22 quad_perm:[1,0,3,2] row_mask:0xf bank_mask:0xf
	v_add_f32_dpp v23, v23, v23 quad_perm:[1,0,3,2] row_mask:0xf bank_mask:0xf
	v_pk_mul_f32 v[84:85], v[2:3], v[40:41] op_sel:[0,0] op_sel_hi:[1,0]
	v_pk_mul_f32 v[86:87], v[4:5], v[40:41] op_sel:[0,1] op_sel_hi:[1,1]
	v_mov_b32_dpp v24, v26 quad_perm:[0,1,2,3] row_mask:0xf bank_mask:0xc
	v_add_f32_dpp v22, v22, v22 quad_perm:[2,3,0,1] row_mask:0xf bank_mask:0xf
	v_add_f32_dpp v23, v23, v23 quad_perm:[2,3,0,1] row_mask:0xf bank_mask:0xf
	v_pk_mul_f32 v[88:89], v[6:7], v[42:43] op_sel:[0,0] op_sel_hi:[1,0]
	v_pk_mul_f32 v[90:91], v[8:9], v[42:43] op_sel:[0,1] op_sel_hi:[1,1]
	v_add_f32_dpp v24, v24, v24 quad_perm:[1,0,3,2] row_mask:0xf bank_mask:0xf
	v_add_f32_dpp v22, v22, v22 row_half_mirror row_mask:0xf bank_mask:0xf
	v_add_f32_dpp v23, v23, v23 row_half_mirror row_mask:0xf bank_mask:0xf
	v_pk_fma_f32 v[84:85], v[48:49], v[56:57], v[84:85] op_sel:[0,0,0] op_sel_hi:[0,1,1]
	v_pk_fma_f32 v[86:87], v[48:49], v[56:57], v[86:87] op_sel:[1,0,0] op_sel_hi:[1,1,1]
	v_add_f32_dpp v24, v24, v24 quad_perm:[2,3,0,1] row_mask:0xf bank_mask:0xf
	v_add_f32_dpp v22, v22, v22 row_mirror row_mask:0xf bank_mask:0xf
	v_add_f32_dpp v23, v23, v23 row_mirror row_mask:0xf bank_mask:0xf
	v_pk_fma_f32 v[88:89], v[50:51], v[56:57], v[88:89] op_sel:[0,0,0] op_sel_hi:[0,1,1]
	v_pk_fma_f32 v[90:91], v[50:51], v[56:57], v[90:91] op_sel:[1,0,0] op_sel_hi:[1,1,1]
	v_cndmask_b32_e64 v30, 0, v24, s[0:1]
	v_pk_fma_f32 v[2:3], v[44:45], v[22:23], v[84:85] op_sel:[0,0,0] op_sel_hi:[0,1,1] neg_lo:[1,0,0] neg_hi:[1,0,0]
	v_pk_fma_f32 v[4:5], v[44:45], v[22:23], v[86:87] op_sel:[1,0,0] op_sel_hi:[1,1,1] neg_lo:[1,0,0] neg_hi:[1,0,0]
	v_pk_fma_f32 v[6:7], v[46:47], v[22:23], v[88:89] op_sel:[0,0,0] op_sel_hi:[0,1,1] neg_lo:[1,0,0] neg_hi:[1,0,0]
	v_pk_fma_f32 v[8:9], v[46:47], v[22:23], v[90:91] op_sel:[1,0,0] op_sel_hi:[1,1,1] neg_lo:[1,0,0] neg_hi:[1,0,0]
	s_waitcnt lgkmcnt(0)
	ds_read_b128 v[36:39], v20 offset:1536
	ds_read_b128 v[40:43], v20 offset:9728
	ds_read_b64 v[56:57], v21 offset:42496
	ds_read_b128 v[48:51], v20 offset:26112
	ds_read_b128 v[44:47], v20 offset:17920
	ds_read_b128 v[52:55], v20 offset:34304
	v_pk_mul_f32 v[22:23], v[2:3], v[60:61] op_sel:[0,0] op_sel_hi:[1,0]
	v_pk_mul_f32 v[24:25], v[2:3], v[76:77] op_sel:[0,0] op_sel_hi:[1,0]
	v_pk_fma_f32 v[22:23], v[4:5], v[60:61], v[22:23] op_sel:[0,1,0] op_sel_hi:[1,1,1]
	v_pk_fma_f32 v[24:25], v[4:5], v[76:77], v[24:25] op_sel:[0,1,0] op_sel_hi:[1,1,1]
	v_pk_fma_f32 v[22:23], v[6:7], v[62:63], v[22:23] op_sel:[0,0,0] op_sel_hi:[1,0,1]
	v_pk_fma_f32 v[24:25], v[6:7], v[78:79], v[24:25] op_sel:[0,0,0] op_sel_hi:[1,0,1]
	v_pk_fma_f32 v[22:23], v[8:9], v[62:63], v[22:23] op_sel:[0,1,0] op_sel_hi:[1,1,1]
	v_pk_fma_f32 v[24:25], v[8:9], v[78:79], v[24:25] op_sel:[0,1,0] op_sel_hi:[1,1,1]
	v_add_f32_dpp v28, v28, v28 row_ror:12 row_mask:0xf bank_mask:0x5
	v_add_f32_dpp v29, v29, v29 row_ror:4 row_mask:0xf bank_mask:0xa
	v_add_f32_dpp v22, v22, v22 quad_perm:[1,0,3,2] row_mask:0xf bank_mask:0xf
	v_add_f32_dpp v23, v23, v23 quad_perm:[1,0,3,2] row_mask:0xf bank_mask:0xf
	v_pk_mul_f32 v[84:85], v[2:3], v[64:65] op_sel:[0,0] op_sel_hi:[1,0]
	v_pk_mul_f32 v[86:87], v[4:5], v[64:65] op_sel:[0,1] op_sel_hi:[1,1]
	v_add_f32_dpp v58, v58, v58 row_ror:12 row_mask:0xf bank_mask:0x5
	v_add_f32_dpp v22, v22, v22 quad_perm:[2,3,0,1] row_mask:0xf bank_mask:0xf
	v_add_f32_dpp v23, v23, v23 quad_perm:[2,3,0,1] row_mask:0xf bank_mask:0xf
	v_pk_mul_f32 v[88:89], v[6:7], v[66:67] op_sel:[0,0] op_sel_hi:[1,0]
	v_pk_mul_f32 v[90:91], v[8:9], v[66:67] op_sel:[0,1] op_sel_hi:[1,1]
	v_add_f32_dpp v59, v59, v59 row_ror:4 row_mask:0xf bank_mask:0xa
	v_add_f32_dpp v22, v22, v22 row_half_mirror row_mask:0xf bank_mask:0xf
	v_add_f32_dpp v23, v23, v23 row_half_mirror row_mask:0xf bank_mask:0xf
	v_pk_fma_f32 v[84:85], v[72:73], v[80:81], v[84:85] op_sel:[0,0,0] op_sel_hi:[0,1,1]
	v_pk_fma_f32 v[86:87], v[72:73], v[80:81], v[86:87] op_sel:[1,0,0] op_sel_hi:[1,1,1]
	v_mov_b32_dpp v28, v29 quad_perm:[0,1,2,3] row_mask:0xf bank_mask:0xa
	v_add_f32_dpp v22, v22, v22 row_mirror row_mask:0xf bank_mask:0xf
	v_add_f32_dpp v23, v23, v23 row_mirror row_mask:0xf bank_mask:0xf
	v_pk_fma_f32 v[88:89], v[74:75], v[80:81], v[88:89] op_sel:[0,0,0] op_sel_hi:[0,1,1]
	v_pk_fma_f32 v[90:91], v[74:75], v[80:81], v[90:91] op_sel:[1,0,0] op_sel_hi:[1,1,1]
	v_mov_b32_dpp v58, v59 quad_perm:[0,1,2,3] row_mask:0xf bank_mask:0xa
	v_pk_fma_f32 v[2:3], v[68:69], v[22:23], v[84:85] op_sel:[0,0,0] op_sel_hi:[0,1,1] neg_lo:[1,0,0] neg_hi:[1,0,0]
	v_pk_fma_f32 v[4:5], v[68:69], v[22:23], v[86:87] op_sel:[1,0,0] op_sel_hi:[1,1,1] neg_lo:[1,0,0] neg_hi:[1,0,0]
	v_pk_fma_f32 v[6:7], v[70:71], v[22:23], v[88:89] op_sel:[0,0,0] op_sel_hi:[0,1,1] neg_lo:[1,0,0] neg_hi:[1,0,0]
	v_pk_fma_f32 v[8:9], v[70:71], v[22:23], v[90:91] op_sel:[1,0,0] op_sel_hi:[1,1,1] neg_lo:[1,0,0] neg_hi:[1,0,0]
	s_waitcnt lgkmcnt(0)
	ds_read_b128 v[60:63], v20 offset:1792
	ds_read_b128 v[64:67], v20 offset:9984
	ds_read_b64 v[80:81], v21 offset:42752
	ds_read_b128 v[72:75], v20 offset:26368
	ds_read_b128 v[68:71], v20 offset:18176
	ds_read_b128 v[76:79], v20 offset:34560
	v_pk_mul_f32 v[22:23], v[2:3], v[36:37] op_sel:[0,0] op_sel_hi:[1,0]
	v_pk_mul_f32 v[26:27], v[2:3], v[92:93] op_sel:[0,0] op_sel_hi:[1,0]
	v_pk_fma_f32 v[22:23], v[4:5], v[36:37], v[22:23] op_sel:[0,1,0] op_sel_hi:[1,1,1]
	v_pk_fma_f32 v[26:27], v[4:5], v[92:93], v[26:27] op_sel:[0,1,0] op_sel_hi:[1,1,1]
	v_pk_fma_f32 v[22:23], v[6:7], v[38:39], v[22:23] op_sel:[0,0,0] op_sel_hi:[1,0,1]
	v_pk_fma_f32 v[26:27], v[6:7], v[94:95], v[26:27] op_sel:[0,0,0] op_sel_hi:[1,0,1]
	v_pk_fma_f32 v[22:23], v[8:9], v[38:39], v[22:23] op_sel:[0,1,0] op_sel_hi:[1,1,1]
	v_pk_fma_f32 v[26:27], v[8:9], v[94:95], v[26:27] op_sel:[0,1,0] op_sel_hi:[1,1,1]
	v_add_f32_dpp v28, v28, v28 row_ror:8 row_mask:0xf bank_mask:0x3
	v_add_f32_dpp v58, v58, v58 row_ror:8 row_mask:0xf bank_mask:0xc
	v_add_f32_dpp v22, v22, v22 quad_perm:[1,0,3,2] row_mask:0xf bank_mask:0xf
	v_add_f32_dpp v23, v23, v23 quad_perm:[1,0,3,2] row_mask:0xf bank_mask:0xf
	v_pk_mul_f32 v[84:85], v[2:3], v[40:41] op_sel:[0,0] op_sel_hi:[1,0]
	v_pk_mul_f32 v[86:87], v[4:5], v[40:41] op_sel:[0,1] op_sel_hi:[1,1]
	v_mov_b32_dpp v28, v58 quad_perm:[0,1,2,3] row_mask:0xf bank_mask:0xc
	v_add_f32_dpp v22, v22, v22 quad_perm:[2,3,0,1] row_mask:0xf bank_mask:0xf
	v_add_f32_dpp v23, v23, v23 quad_perm:[2,3,0,1] row_mask:0xf bank_mask:0xf
	v_pk_mul_f32 v[88:89], v[6:7], v[42:43] op_sel:[0,0] op_sel_hi:[1,0]
	v_pk_mul_f32 v[90:91], v[8:9], v[42:43] op_sel:[0,1] op_sel_hi:[1,1]
	v_add_f32_dpp v28, v28, v28 quad_perm:[1,0,3,2] row_mask:0xf bank_mask:0xf
	v_add_f32_dpp v22, v22, v22 row_half_mirror row_mask:0xf bank_mask:0xf
	v_add_f32_dpp v23, v23, v23 row_half_mirror row_mask:0xf bank_mask:0xf
	v_pk_fma_f32 v[84:85], v[48:49], v[56:57], v[84:85] op_sel:[0,0,0] op_sel_hi:[0,1,1]
	v_pk_fma_f32 v[86:87], v[48:49], v[56:57], v[86:87] op_sel:[1,0,0] op_sel_hi:[1,1,1]
	v_add_f32_dpp v28, v28, v28 quad_perm:[2,3,0,1] row_mask:0xf bank_mask:0xf
	v_add_f32_dpp v22, v22, v22 row_mirror row_mask:0xf bank_mask:0xf
	v_add_f32_dpp v23, v23, v23 row_mirror row_mask:0xf bank_mask:0xf
	v_pk_fma_f32 v[88:89], v[50:51], v[56:57], v[88:89] op_sel:[0,0,0] op_sel_hi:[0,1,1]
	v_pk_fma_f32 v[90:91], v[50:51], v[56:57], v[90:91] op_sel:[1,0,0] op_sel_hi:[1,1,1]
	v_cndmask_b32_e64 v30, v30, v28, s[6:7]
	v_pk_fma_f32 v[2:3], v[44:45], v[22:23], v[84:85] op_sel:[0,0,0] op_sel_hi:[0,1,1] neg_lo:[1,0,0] neg_hi:[1,0,0]
	v_pk_fma_f32 v[4:5], v[44:45], v[22:23], v[86:87] op_sel:[1,0,0] op_sel_hi:[1,1,1] neg_lo:[1,0,0] neg_hi:[1,0,0]
	v_pk_fma_f32 v[6:7], v[46:47], v[22:23], v[88:89] op_sel:[0,0,0] op_sel_hi:[0,1,1] neg_lo:[1,0,0] neg_hi:[1,0,0]
	v_pk_fma_f32 v[8:9], v[46:47], v[22:23], v[90:91] op_sel:[1,0,0] op_sel_hi:[1,1,1] neg_lo:[1,0,0] neg_hi:[1,0,0]
	s_waitcnt lgkmcnt(0)
	ds_read_b128 v[36:39], v20 offset:2048
	ds_read_b128 v[40:43], v20 offset:10240
	ds_read_b64 v[56:57], v21 offset:43008
	ds_read_b128 v[48:51], v20 offset:26624
	ds_read_b128 v[44:47], v20 offset:18432
	ds_read_b128 v[92:95], v20 offset:34816
	v_pk_mul_f32 v[22:23], v[2:3], v[60:61] op_sel:[0,0] op_sel_hi:[1,0]
	v_pk_mul_f32 v[28:29], v[2:3], v[52:53] op_sel:[0,0] op_sel_hi:[1,0]
	v_pk_fma_f32 v[22:23], v[4:5], v[60:61], v[22:23] op_sel:[0,1,0] op_sel_hi:[1,1,1]
	v_pk_fma_f32 v[28:29], v[4:5], v[52:53], v[28:29] op_sel:[0,1,0] op_sel_hi:[1,1,1]
	v_pk_fma_f32 v[22:23], v[6:7], v[62:63], v[22:23] op_sel:[0,0,0] op_sel_hi:[1,0,1]
	v_pk_fma_f32 v[28:29], v[6:7], v[54:55], v[28:29] op_sel:[0,0,0] op_sel_hi:[1,0,1]
	v_pk_fma_f32 v[22:23], v[8:9], v[62:63], v[22:23] op_sel:[0,1,0] op_sel_hi:[1,1,1]
	v_pk_fma_f32 v[28:29], v[8:9], v[54:55], v[28:29] op_sel:[0,1,0] op_sel_hi:[1,1,1]
	v_add_f32_dpp v24, v24, v24 row_ror:12 row_mask:0xf bank_mask:0x5
	v_add_f32_dpp v25, v25, v25 row_ror:4 row_mask:0xf bank_mask:0xa
	v_add_f32_dpp v22, v22, v22 quad_perm:[1,0,3,2] row_mask:0xf bank_mask:0xf
	v_add_f32_dpp v23, v23, v23 quad_perm:[1,0,3,2] row_mask:0xf bank_mask:0xf
	v_pk_mul_f32 v[84:85], v[2:3], v[64:65] op_sel:[0,0] op_sel_hi:[1,0]
	v_pk_mul_f32 v[86:87], v[4:5], v[64:65] op_sel:[0,1] op_sel_hi:[1,1]
	v_add_f32_dpp v26, v26, v26 row_ror:12 row_mask:0xf bank_mask:0x5
	v_add_f32_dpp v22, v22, v22 quad_perm:[2,3,0,1] row_mask:0xf bank_mask:0xf
	v_add_f32_dpp v23, v23, v23 quad_perm:[2,3,0,1] row_mask:0xf bank_mask:0xf
	v_pk_mul_f32 v[88:89], v[6:7], v[66:67] op_sel:[0,0] op_sel_hi:[1,0]
	v_pk_mul_f32 v[90:91], v[8:9], v[66:67] op_sel:[0,1] op_sel_hi:[1,1]
	v_add_f32_dpp v27, v27, v27 row_ror:4 row_mask:0xf bank_mask:0xa
	v_add_f32_dpp v22, v22, v22 row_half_mirror row_mask:0xf bank_mask:0xf
	v_add_f32_dpp v23, v23, v23 row_half_mirror row_mask:0xf bank_mask:0xf
	v_pk_fma_f32 v[84:85], v[72:73], v[80:81], v[84:85] op_sel:[0,0,0] op_sel_hi:[0,1,1]
	v_pk_fma_f32 v[86:87], v[72:73], v[80:81], v[86:87] op_sel:[1,0,0] op_sel_hi:[1,1,1]
	v_mov_b32_dpp v24, v25 quad_perm:[0,1,2,3] row_mask:0xf bank_mask:0xa
	v_add_f32_dpp v22, v22, v22 row_mirror row_mask:0xf bank_mask:0xf
	v_add_f32_dpp v23, v23, v23 row_mirror row_mask:0xf bank_mask:0xf
	v_pk_fma_f32 v[88:89], v[74:75], v[80:81], v[88:89] op_sel:[0,0,0] op_sel_hi:[0,1,1]
	v_pk_fma_f32 v[90:91], v[74:75], v[80:81], v[90:91] op_sel:[1,0,0] op_sel_hi:[1,1,1]
	v_mov_b32_dpp v26, v27 quad_perm:[0,1,2,3] row_mask:0xf bank_mask:0xa
	v_pk_fma_f32 v[2:3], v[68:69], v[22:23], v[84:85] op_sel:[0,0,0] op_sel_hi:[0,1,1] neg_lo:[1,0,0] neg_hi:[1,0,0]
	v_pk_fma_f32 v[4:5], v[68:69], v[22:23], v[86:87] op_sel:[1,0,0] op_sel_hi:[1,1,1] neg_lo:[1,0,0] neg_hi:[1,0,0]
	v_pk_fma_f32 v[6:7], v[70:71], v[22:23], v[88:89] op_sel:[0,0,0] op_sel_hi:[0,1,1] neg_lo:[1,0,0] neg_hi:[1,0,0]
	v_pk_fma_f32 v[8:9], v[70:71], v[22:23], v[90:91] op_sel:[1,0,0] op_sel_hi:[1,1,1] neg_lo:[1,0,0] neg_hi:[1,0,0]
	s_waitcnt lgkmcnt(0)
	ds_read_b128 v[60:63], v20 offset:2304
	ds_read_b128 v[64:67], v20 offset:10496
	ds_read_b64 v[80:81], v21 offset:43264
	ds_read_b128 v[72:75], v20 offset:26880
	ds_read_b128 v[68:71], v20 offset:18688
	ds_read_b128 v[52:55], v20 offset:35072
	v_pk_mul_f32 v[22:23], v[2:3], v[36:37] op_sel:[0,0] op_sel_hi:[1,0]
	v_pk_mul_f32 v[58:59], v[2:3], v[76:77] op_sel:[0,0] op_sel_hi:[1,0]
	v_pk_fma_f32 v[22:23], v[4:5], v[36:37], v[22:23] op_sel:[0,1,0] op_sel_hi:[1,1,1]
	v_pk_fma_f32 v[58:59], v[4:5], v[76:77], v[58:59] op_sel:[0,1,0] op_sel_hi:[1,1,1]
	v_pk_fma_f32 v[22:23], v[6:7], v[38:39], v[22:23] op_sel:[0,0,0] op_sel_hi:[1,0,1]
	v_pk_fma_f32 v[58:59], v[6:7], v[78:79], v[58:59] op_sel:[0,0,0] op_sel_hi:[1,0,1]
	v_pk_fma_f32 v[22:23], v[8:9], v[38:39], v[22:23] op_sel:[0,1,0] op_sel_hi:[1,1,1]
	v_pk_fma_f32 v[58:59], v[8:9], v[78:79], v[58:59] op_sel:[0,1,0] op_sel_hi:[1,1,1]
	v_add_f32_dpp v24, v24, v24 row_ror:8 row_mask:0xf bank_mask:0x3
	v_add_f32_dpp v26, v26, v26 row_ror:8 row_mask:0xf bank_mask:0xc
	v_add_f32_dpp v22, v22, v22 quad_perm:[1,0,3,2] row_mask:0xf bank_mask:0xf
	v_add_f32_dpp v23, v23, v23 quad_perm:[1,0,3,2] row_mask:0xf bank_mask:0xf
	v_pk_mul_f32 v[84:85], v[2:3], v[40:41] op_sel:[0,0] op_sel_hi:[1,0]
	v_pk_mul_f32 v[86:87], v[4:5], v[40:41] op_sel:[0,1] op_sel_hi:[1,1]
	v_mov_b32_dpp v24, v26 quad_perm:[0,1,2,3] row_mask:0xf bank_mask:0xc
	v_add_f32_dpp v22, v22, v22 quad_perm:[2,3,0,1] row_mask:0xf bank_mask:0xf
	v_add_f32_dpp v23, v23, v23 quad_perm:[2,3,0,1] row_mask:0xf bank_mask:0xf
	v_pk_mul_f32 v[88:89], v[6:7], v[42:43] op_sel:[0,0] op_sel_hi:[1,0]
	v_pk_mul_f32 v[90:91], v[8:9], v[42:43] op_sel:[0,1] op_sel_hi:[1,1]
	v_add_f32_dpp v24, v24, v24 quad_perm:[1,0,3,2] row_mask:0xf bank_mask:0xf
	v_add_f32_dpp v22, v22, v22 row_half_mirror row_mask:0xf bank_mask:0xf
	v_add_f32_dpp v23, v23, v23 row_half_mirror row_mask:0xf bank_mask:0xf
	v_pk_fma_f32 v[84:85], v[48:49], v[56:57], v[84:85] op_sel:[0,0,0] op_sel_hi:[0,1,1]
	v_pk_fma_f32 v[86:87], v[48:49], v[56:57], v[86:87] op_sel:[1,0,0] op_sel_hi:[1,1,1]
	v_add_f32_dpp v24, v24, v24 quad_perm:[2,3,0,1] row_mask:0xf bank_mask:0xf
	v_add_f32_dpp v22, v22, v22 row_mirror row_mask:0xf bank_mask:0xf
	v_add_f32_dpp v23, v23, v23 row_mirror row_mask:0xf bank_mask:0xf
	v_pk_fma_f32 v[88:89], v[50:51], v[56:57], v[88:89] op_sel:[0,0,0] op_sel_hi:[0,1,1]
	v_pk_fma_f32 v[90:91], v[50:51], v[56:57], v[90:91] op_sel:[1,0,0] op_sel_hi:[1,1,1]
	v_cndmask_b32_e64 v30, v30, v24, s[8:9]
	v_pk_fma_f32 v[2:3], v[44:45], v[22:23], v[84:85] op_sel:[0,0,0] op_sel_hi:[0,1,1] neg_lo:[1,0,0] neg_hi:[1,0,0]
	v_pk_fma_f32 v[4:5], v[44:45], v[22:23], v[86:87] op_sel:[1,0,0] op_sel_hi:[1,1,1] neg_lo:[1,0,0] neg_hi:[1,0,0]
	v_pk_fma_f32 v[6:7], v[46:47], v[22:23], v[88:89] op_sel:[0,0,0] op_sel_hi:[0,1,1] neg_lo:[1,0,0] neg_hi:[1,0,0]
	v_pk_fma_f32 v[8:9], v[46:47], v[22:23], v[90:91] op_sel:[1,0,0] op_sel_hi:[1,1,1] neg_lo:[1,0,0] neg_hi:[1,0,0]
	s_waitcnt lgkmcnt(0)
	ds_read_b128 v[36:39], v20 offset:2560
	ds_read_b128 v[40:43], v20 offset:10752
	ds_read_b64 v[56:57], v21 offset:43520
	ds_read_b128 v[48:51], v20 offset:27136
	ds_read_b128 v[44:47], v20 offset:18944
	ds_read_b128 v[76:79], v20 offset:35328
	v_pk_mul_f32 v[22:23], v[2:3], v[60:61] op_sel:[0,0] op_sel_hi:[1,0]
	v_pk_mul_f32 v[24:25], v[2:3], v[92:93] op_sel:[0,0] op_sel_hi:[1,0]
	v_pk_fma_f32 v[22:23], v[4:5], v[60:61], v[22:23] op_sel:[0,1,0] op_sel_hi:[1,1,1]
	v_pk_fma_f32 v[24:25], v[4:5], v[92:93], v[24:25] op_sel:[0,1,0] op_sel_hi:[1,1,1]
	v_pk_fma_f32 v[22:23], v[6:7], v[62:63], v[22:23] op_sel:[0,0,0] op_sel_hi:[1,0,1]
	v_pk_fma_f32 v[24:25], v[6:7], v[94:95], v[24:25] op_sel:[0,0,0] op_sel_hi:[1,0,1]
	v_pk_fma_f32 v[22:23], v[8:9], v[62:63], v[22:23] op_sel:[0,1,0] op_sel_hi:[1,1,1]
	v_pk_fma_f32 v[24:25], v[8:9], v[94:95], v[24:25] op_sel:[0,1,0] op_sel_hi:[1,1,1]
	v_add_f32_dpp v28, v28, v28 row_ror:12 row_mask:0xf bank_mask:0x5
	v_add_f32_dpp v29, v29, v29 row_ror:4 row_mask:0xf bank_mask:0xa
	v_add_f32_dpp v22, v22, v22 quad_perm:[1,0,3,2] row_mask:0xf bank_mask:0xf
	v_add_f32_dpp v23, v23, v23 quad_perm:[1,0,3,2] row_mask:0xf bank_mask:0xf
	v_pk_mul_f32 v[84:85], v[2:3], v[64:65] op_sel:[0,0] op_sel_hi:[1,0]
	v_pk_mul_f32 v[86:87], v[4:5], v[64:65] op_sel:[0,1] op_sel_hi:[1,1]
	v_add_f32_dpp v58, v58, v58 row_ror:12 row_mask:0xf bank_mask:0x5
	v_add_f32_dpp v22, v22, v22 quad_perm:[2,3,0,1] row_mask:0xf bank_mask:0xf
	v_add_f32_dpp v23, v23, v23 quad_perm:[2,3,0,1] row_mask:0xf bank_mask:0xf
	v_pk_mul_f32 v[88:89], v[6:7], v[66:67] op_sel:[0,0] op_sel_hi:[1,0]
	v_pk_mul_f32 v[90:91], v[8:9], v[66:67] op_sel:[0,1] op_sel_hi:[1,1]
	v_add_f32_dpp v59, v59, v59 row_ror:4 row_mask:0xf bank_mask:0xa
	v_add_f32_dpp v22, v22, v22 row_half_mirror row_mask:0xf bank_mask:0xf
	v_add_f32_dpp v23, v23, v23 row_half_mirror row_mask:0xf bank_mask:0xf
	v_pk_fma_f32 v[84:85], v[72:73], v[80:81], v[84:85] op_sel:[0,0,0] op_sel_hi:[0,1,1]
	v_pk_fma_f32 v[86:87], v[72:73], v[80:81], v[86:87] op_sel:[1,0,0] op_sel_hi:[1,1,1]
	v_mov_b32_dpp v28, v29 quad_perm:[0,1,2,3] row_mask:0xf bank_mask:0xa
	v_add_f32_dpp v22, v22, v22 row_mirror row_mask:0xf bank_mask:0xf
	v_add_f32_dpp v23, v23, v23 row_mirror row_mask:0xf bank_mask:0xf
	v_pk_fma_f32 v[88:89], v[74:75], v[80:81], v[88:89] op_sel:[0,0,0] op_sel_hi:[0,1,1]
	v_pk_fma_f32 v[90:91], v[74:75], v[80:81], v[90:91] op_sel:[1,0,0] op_sel_hi:[1,1,1]
	v_mov_b32_dpp v58, v59 quad_perm:[0,1,2,3] row_mask:0xf bank_mask:0xa
	v_pk_fma_f32 v[2:3], v[68:69], v[22:23], v[84:85] op_sel:[0,0,0] op_sel_hi:[0,1,1] neg_lo:[1,0,0] neg_hi:[1,0,0]
	v_pk_fma_f32 v[4:5], v[68:69], v[22:23], v[86:87] op_sel:[1,0,0] op_sel_hi:[1,1,1] neg_lo:[1,0,0] neg_hi:[1,0,0]
	v_pk_fma_f32 v[6:7], v[70:71], v[22:23], v[88:89] op_sel:[0,0,0] op_sel_hi:[0,1,1] neg_lo:[1,0,0] neg_hi:[1,0,0]
	v_pk_fma_f32 v[8:9], v[70:71], v[22:23], v[90:91] op_sel:[1,0,0] op_sel_hi:[1,1,1] neg_lo:[1,0,0] neg_hi:[1,0,0]
	s_waitcnt lgkmcnt(0)
	ds_read_b128 v[60:63], v20 offset:2816
	ds_read_b128 v[64:67], v20 offset:11008
	ds_read_b64 v[80:81], v21 offset:43776
	ds_read_b128 v[72:75], v20 offset:27392
	ds_read_b128 v[68:71], v20 offset:19200
	ds_read_b128 v[92:95], v20 offset:35584
	v_pk_mul_f32 v[22:23], v[2:3], v[36:37] op_sel:[0,0] op_sel_hi:[1,0]
	v_pk_mul_f32 v[26:27], v[2:3], v[52:53] op_sel:[0,0] op_sel_hi:[1,0]
	v_pk_fma_f32 v[22:23], v[4:5], v[36:37], v[22:23] op_sel:[0,1,0] op_sel_hi:[1,1,1]
	v_pk_fma_f32 v[26:27], v[4:5], v[52:53], v[26:27] op_sel:[0,1,0] op_sel_hi:[1,1,1]
	v_pk_fma_f32 v[22:23], v[6:7], v[38:39], v[22:23] op_sel:[0,0,0] op_sel_hi:[1,0,1]
	v_pk_fma_f32 v[26:27], v[6:7], v[54:55], v[26:27] op_sel:[0,0,0] op_sel_hi:[1,0,1]
	v_pk_fma_f32 v[22:23], v[8:9], v[38:39], v[22:23] op_sel:[0,1,0] op_sel_hi:[1,1,1]
	v_pk_fma_f32 v[26:27], v[8:9], v[54:55], v[26:27] op_sel:[0,1,0] op_sel_hi:[1,1,1]
	v_add_f32_dpp v28, v28, v28 row_ror:8 row_mask:0xf bank_mask:0x3
	v_add_f32_dpp v58, v58, v58 row_ror:8 row_mask:0xf bank_mask:0xc
	v_add_f32_dpp v22, v22, v22 quad_perm:[1,0,3,2] row_mask:0xf bank_mask:0xf
	v_add_f32_dpp v23, v23, v23 quad_perm:[1,0,3,2] row_mask:0xf bank_mask:0xf
	v_pk_mul_f32 v[84:85], v[2:3], v[40:41] op_sel:[0,0] op_sel_hi:[1,0]
	v_pk_mul_f32 v[86:87], v[4:5], v[40:41] op_sel:[0,1] op_sel_hi:[1,1]
	v_mov_b32_dpp v28, v58 quad_perm:[0,1,2,3] row_mask:0xf bank_mask:0xc
	v_add_f32_dpp v22, v22, v22 quad_perm:[2,3,0,1] row_mask:0xf bank_mask:0xf
	v_add_f32_dpp v23, v23, v23 quad_perm:[2,3,0,1] row_mask:0xf bank_mask:0xf
	v_pk_mul_f32 v[88:89], v[6:7], v[42:43] op_sel:[0,0] op_sel_hi:[1,0]
	v_pk_mul_f32 v[90:91], v[8:9], v[42:43] op_sel:[0,1] op_sel_hi:[1,1]
	v_add_f32_dpp v28, v28, v28 quad_perm:[1,0,3,2] row_mask:0xf bank_mask:0xf
	v_add_f32_dpp v22, v22, v22 row_half_mirror row_mask:0xf bank_mask:0xf
	v_add_f32_dpp v23, v23, v23 row_half_mirror row_mask:0xf bank_mask:0xf
	v_pk_fma_f32 v[84:85], v[48:49], v[56:57], v[84:85] op_sel:[0,0,0] op_sel_hi:[0,1,1]
	v_pk_fma_f32 v[86:87], v[48:49], v[56:57], v[86:87] op_sel:[1,0,0] op_sel_hi:[1,1,1]
	v_add_f32_dpp v28, v28, v28 quad_perm:[2,3,0,1] row_mask:0xf bank_mask:0xf
	v_add_f32_dpp v22, v22, v22 row_mirror row_mask:0xf bank_mask:0xf
	v_add_f32_dpp v23, v23, v23 row_mirror row_mask:0xf bank_mask:0xf
	v_pk_fma_f32 v[88:89], v[50:51], v[56:57], v[88:89] op_sel:[0,0,0] op_sel_hi:[0,1,1]
	v_pk_fma_f32 v[90:91], v[50:51], v[56:57], v[90:91] op_sel:[1,0,0] op_sel_hi:[1,1,1]
	v_cndmask_b32_e64 v30, v30, v28, s[10:11]
	v_pk_fma_f32 v[2:3], v[44:45], v[22:23], v[84:85] op_sel:[0,0,0] op_sel_hi:[0,1,1] neg_lo:[1,0,0] neg_hi:[1,0,0]
	v_pk_fma_f32 v[4:5], v[44:45], v[22:23], v[86:87] op_sel:[1,0,0] op_sel_hi:[1,1,1] neg_lo:[1,0,0] neg_hi:[1,0,0]
	v_pk_fma_f32 v[6:7], v[46:47], v[22:23], v[88:89] op_sel:[0,0,0] op_sel_hi:[0,1,1] neg_lo:[1,0,0] neg_hi:[1,0,0]
	v_pk_fma_f32 v[8:9], v[46:47], v[22:23], v[90:91] op_sel:[1,0,0] op_sel_hi:[1,1,1] neg_lo:[1,0,0] neg_hi:[1,0,0]
	s_waitcnt lgkmcnt(0)
	ds_read_b128 v[36:39], v20 offset:3072
	ds_read_b128 v[40:43], v20 offset:11264
	ds_read_b64 v[56:57], v21 offset:44032
	ds_read_b128 v[48:51], v20 offset:27648
	ds_read_b128 v[44:47], v20 offset:19456
	ds_read_b128 v[52:55], v20 offset:35840
	v_pk_mul_f32 v[22:23], v[2:3], v[60:61] op_sel:[0,0] op_sel_hi:[1,0]
	v_pk_mul_f32 v[28:29], v[2:3], v[76:77] op_sel:[0,0] op_sel_hi:[1,0]
	v_pk_fma_f32 v[22:23], v[4:5], v[60:61], v[22:23] op_sel:[0,1,0] op_sel_hi:[1,1,1]
	v_pk_fma_f32 v[28:29], v[4:5], v[76:77], v[28:29] op_sel:[0,1,0] op_sel_hi:[1,1,1]
	v_pk_fma_f32 v[22:23], v[6:7], v[62:63], v[22:23] op_sel:[0,0,0] op_sel_hi:[1,0,1]
	v_pk_fma_f32 v[28:29], v[6:7], v[78:79], v[28:29] op_sel:[0,0,0] op_sel_hi:[1,0,1]
	v_pk_fma_f32 v[22:23], v[8:9], v[62:63], v[22:23] op_sel:[0,1,0] op_sel_hi:[1,1,1]
	v_pk_fma_f32 v[28:29], v[8:9], v[78:79], v[28:29] op_sel:[0,1,0] op_sel_hi:[1,1,1]
	v_add_f32_dpp v24, v24, v24 row_ror:12 row_mask:0xf bank_mask:0x5
	v_add_f32_dpp v25, v25, v25 row_ror:4 row_mask:0xf bank_mask:0xa
	v_add_f32_dpp v22, v22, v22 quad_perm:[1,0,3,2] row_mask:0xf bank_mask:0xf
	v_add_f32_dpp v23, v23, v23 quad_perm:[1,0,3,2] row_mask:0xf bank_mask:0xf
	v_pk_mul_f32 v[84:85], v[2:3], v[64:65] op_sel:[0,0] op_sel_hi:[1,0]
	v_pk_mul_f32 v[86:87], v[4:5], v[64:65] op_sel:[0,1] op_sel_hi:[1,1]
	v_add_f32_dpp v26, v26, v26 row_ror:12 row_mask:0xf bank_mask:0x5
	v_add_f32_dpp v22, v22, v22 quad_perm:[2,3,0,1] row_mask:0xf bank_mask:0xf
	v_add_f32_dpp v23, v23, v23 quad_perm:[2,3,0,1] row_mask:0xf bank_mask:0xf
	v_pk_mul_f32 v[88:89], v[6:7], v[66:67] op_sel:[0,0] op_sel_hi:[1,0]
	v_pk_mul_f32 v[90:91], v[8:9], v[66:67] op_sel:[0,1] op_sel_hi:[1,1]
	v_add_f32_dpp v27, v27, v27 row_ror:4 row_mask:0xf bank_mask:0xa
	v_add_f32_dpp v22, v22, v22 row_half_mirror row_mask:0xf bank_mask:0xf
	v_add_f32_dpp v23, v23, v23 row_half_mirror row_mask:0xf bank_mask:0xf
	v_pk_fma_f32 v[84:85], v[72:73], v[80:81], v[84:85] op_sel:[0,0,0] op_sel_hi:[0,1,1]
	v_pk_fma_f32 v[86:87], v[72:73], v[80:81], v[86:87] op_sel:[1,0,0] op_sel_hi:[1,1,1]
	v_mov_b32_dpp v24, v25 quad_perm:[0,1,2,3] row_mask:0xf bank_mask:0xa
	v_add_f32_dpp v22, v22, v22 row_mirror row_mask:0xf bank_mask:0xf
	v_add_f32_dpp v23, v23, v23 row_mirror row_mask:0xf bank_mask:0xf
	v_pk_fma_f32 v[88:89], v[74:75], v[80:81], v[88:89] op_sel:[0,0,0] op_sel_hi:[0,1,1]
	v_pk_fma_f32 v[90:91], v[74:75], v[80:81], v[90:91] op_sel:[1,0,0] op_sel_hi:[1,1,1]
	v_mov_b32_dpp v26, v27 quad_perm:[0,1,2,3] row_mask:0xf bank_mask:0xa
	v_pk_fma_f32 v[2:3], v[68:69], v[22:23], v[84:85] op_sel:[0,0,0] op_sel_hi:[0,1,1] neg_lo:[1,0,0] neg_hi:[1,0,0]
	v_pk_fma_f32 v[4:5], v[68:69], v[22:23], v[86:87] op_sel:[1,0,0] op_sel_hi:[1,1,1] neg_lo:[1,0,0] neg_hi:[1,0,0]
	v_pk_fma_f32 v[6:7], v[70:71], v[22:23], v[88:89] op_sel:[0,0,0] op_sel_hi:[0,1,1] neg_lo:[1,0,0] neg_hi:[1,0,0]
	v_pk_fma_f32 v[8:9], v[70:71], v[22:23], v[90:91] op_sel:[1,0,0] op_sel_hi:[1,1,1] neg_lo:[1,0,0] neg_hi:[1,0,0]
	s_waitcnt lgkmcnt(0)
	ds_read_b128 v[60:63], v20 offset:3328
	ds_read_b128 v[64:67], v20 offset:11520
	ds_read_b64 v[80:81], v21 offset:44288
	ds_read_b128 v[72:75], v20 offset:27904
	ds_read_b128 v[68:71], v20 offset:19712
	ds_read_b128 v[76:79], v20 offset:36096
	v_pk_mul_f32 v[22:23], v[2:3], v[36:37] op_sel:[0,0] op_sel_hi:[1,0]
	v_pk_mul_f32 v[58:59], v[2:3], v[92:93] op_sel:[0,0] op_sel_hi:[1,0]
	v_pk_fma_f32 v[22:23], v[4:5], v[36:37], v[22:23] op_sel:[0,1,0] op_sel_hi:[1,1,1]
	v_pk_fma_f32 v[58:59], v[4:5], v[92:93], v[58:59] op_sel:[0,1,0] op_sel_hi:[1,1,1]
	v_pk_fma_f32 v[22:23], v[6:7], v[38:39], v[22:23] op_sel:[0,0,0] op_sel_hi:[1,0,1]
	v_pk_fma_f32 v[58:59], v[6:7], v[94:95], v[58:59] op_sel:[0,0,0] op_sel_hi:[1,0,1]
	v_pk_fma_f32 v[22:23], v[8:9], v[38:39], v[22:23] op_sel:[0,1,0] op_sel_hi:[1,1,1]
	v_pk_fma_f32 v[58:59], v[8:9], v[94:95], v[58:59] op_sel:[0,1,0] op_sel_hi:[1,1,1]
	v_add_f32_dpp v24, v24, v24 row_ror:8 row_mask:0xf bank_mask:0x3
	v_add_f32_dpp v26, v26, v26 row_ror:8 row_mask:0xf bank_mask:0xc
	v_add_f32_dpp v22, v22, v22 quad_perm:[1,0,3,2] row_mask:0xf bank_mask:0xf
	v_add_f32_dpp v23, v23, v23 quad_perm:[1,0,3,2] row_mask:0xf bank_mask:0xf
	v_pk_mul_f32 v[84:85], v[2:3], v[40:41] op_sel:[0,0] op_sel_hi:[1,0]
	v_pk_mul_f32 v[86:87], v[4:5], v[40:41] op_sel:[0,1] op_sel_hi:[1,1]
	v_mov_b32_dpp v24, v26 quad_perm:[0,1,2,3] row_mask:0xf bank_mask:0xc
	v_add_f32_dpp v22, v22, v22 quad_perm:[2,3,0,1] row_mask:0xf bank_mask:0xf
	v_add_f32_dpp v23, v23, v23 quad_perm:[2,3,0,1] row_mask:0xf bank_mask:0xf
	v_pk_mul_f32 v[88:89], v[6:7], v[42:43] op_sel:[0,0] op_sel_hi:[1,0]
	v_pk_mul_f32 v[90:91], v[8:9], v[42:43] op_sel:[0,1] op_sel_hi:[1,1]
	v_add_f32_dpp v24, v24, v24 quad_perm:[1,0,3,2] row_mask:0xf bank_mask:0xf
	v_add_f32_dpp v22, v22, v22 row_half_mirror row_mask:0xf bank_mask:0xf
	v_add_f32_dpp v23, v23, v23 row_half_mirror row_mask:0xf bank_mask:0xf
	v_pk_fma_f32 v[84:85], v[48:49], v[56:57], v[84:85] op_sel:[0,0,0] op_sel_hi:[0,1,1]
	v_pk_fma_f32 v[86:87], v[48:49], v[56:57], v[86:87] op_sel:[1,0,0] op_sel_hi:[1,1,1]
	v_add_f32_dpp v24, v24, v24 quad_perm:[2,3,0,1] row_mask:0xf bank_mask:0xf
	v_add_f32_dpp v22, v22, v22 row_mirror row_mask:0xf bank_mask:0xf
	v_add_f32_dpp v23, v23, v23 row_mirror row_mask:0xf bank_mask:0xf
	v_pk_fma_f32 v[88:89], v[50:51], v[56:57], v[88:89] op_sel:[0,0,0] op_sel_hi:[0,1,1]
	v_pk_fma_f32 v[90:91], v[50:51], v[56:57], v[90:91] op_sel:[1,0,0] op_sel_hi:[1,1,1]
	v_cndmask_b32_e64 v31, 0, v24, s[0:1]
	v_pk_fma_f32 v[2:3], v[44:45], v[22:23], v[84:85] op_sel:[0,0,0] op_sel_hi:[0,1,1] neg_lo:[1,0,0] neg_hi:[1,0,0]
	v_pk_fma_f32 v[4:5], v[44:45], v[22:23], v[86:87] op_sel:[1,0,0] op_sel_hi:[1,1,1] neg_lo:[1,0,0] neg_hi:[1,0,0]
	v_pk_fma_f32 v[6:7], v[46:47], v[22:23], v[88:89] op_sel:[0,0,0] op_sel_hi:[0,1,1] neg_lo:[1,0,0] neg_hi:[1,0,0]
	v_pk_fma_f32 v[8:9], v[46:47], v[22:23], v[90:91] op_sel:[1,0,0] op_sel_hi:[1,1,1] neg_lo:[1,0,0] neg_hi:[1,0,0]
	s_waitcnt lgkmcnt(0)
	ds_read_b128 v[36:39], v20 offset:3584
	ds_read_b128 v[40:43], v20 offset:11776
	ds_read_b64 v[56:57], v21 offset:44544
	ds_read_b128 v[48:51], v20 offset:28160
	ds_read_b128 v[44:47], v20 offset:19968
	ds_read_b128 v[92:95], v20 offset:36352
	v_pk_mul_f32 v[22:23], v[2:3], v[60:61] op_sel:[0,0] op_sel_hi:[1,0]
	v_pk_mul_f32 v[24:25], v[2:3], v[52:53] op_sel:[0,0] op_sel_hi:[1,0]
	v_pk_fma_f32 v[22:23], v[4:5], v[60:61], v[22:23] op_sel:[0,1,0] op_sel_hi:[1,1,1]
	v_pk_fma_f32 v[24:25], v[4:5], v[52:53], v[24:25] op_sel:[0,1,0] op_sel_hi:[1,1,1]
	v_pk_fma_f32 v[22:23], v[6:7], v[62:63], v[22:23] op_sel:[0,0,0] op_sel_hi:[1,0,1]
	v_pk_fma_f32 v[24:25], v[6:7], v[54:55], v[24:25] op_sel:[0,0,0] op_sel_hi:[1,0,1]
	v_pk_fma_f32 v[22:23], v[8:9], v[62:63], v[22:23] op_sel:[0,1,0] op_sel_hi:[1,1,1]
	v_pk_fma_f32 v[24:25], v[8:9], v[54:55], v[24:25] op_sel:[0,1,0] op_sel_hi:[1,1,1]
	v_add_f32_dpp v28, v28, v28 row_ror:12 row_mask:0xf bank_mask:0x5
	v_add_f32_dpp v29, v29, v29 row_ror:4 row_mask:0xf bank_mask:0xa
	v_add_f32_dpp v22, v22, v22 quad_perm:[1,0,3,2] row_mask:0xf bank_mask:0xf
	v_add_f32_dpp v23, v23, v23 quad_perm:[1,0,3,2] row_mask:0xf bank_mask:0xf
	v_pk_mul_f32 v[84:85], v[2:3], v[64:65] op_sel:[0,0] op_sel_hi:[1,0]
	v_pk_mul_f32 v[86:87], v[4:5], v[64:65] op_sel:[0,1] op_sel_hi:[1,1]
	v_add_f32_dpp v58, v58, v58 row_ror:12 row_mask:0xf bank_mask:0x5
	v_add_f32_dpp v22, v22, v22 quad_perm:[2,3,0,1] row_mask:0xf bank_mask:0xf
	v_add_f32_dpp v23, v23, v23 quad_perm:[2,3,0,1] row_mask:0xf bank_mask:0xf
	v_pk_mul_f32 v[88:89], v[6:7], v[66:67] op_sel:[0,0] op_sel_hi:[1,0]
	v_pk_mul_f32 v[90:91], v[8:9], v[66:67] op_sel:[0,1] op_sel_hi:[1,1]
	v_add_f32_dpp v59, v59, v59 row_ror:4 row_mask:0xf bank_mask:0xa
	v_add_f32_dpp v22, v22, v22 row_half_mirror row_mask:0xf bank_mask:0xf
	v_add_f32_dpp v23, v23, v23 row_half_mirror row_mask:0xf bank_mask:0xf
	v_pk_fma_f32 v[84:85], v[72:73], v[80:81], v[84:85] op_sel:[0,0,0] op_sel_hi:[0,1,1]
	v_pk_fma_f32 v[86:87], v[72:73], v[80:81], v[86:87] op_sel:[1,0,0] op_sel_hi:[1,1,1]
	v_mov_b32_dpp v28, v29 quad_perm:[0,1,2,3] row_mask:0xf bank_mask:0xa
	v_add_f32_dpp v22, v22, v22 row_mirror row_mask:0xf bank_mask:0xf
	v_add_f32_dpp v23, v23, v23 row_mirror row_mask:0xf bank_mask:0xf
	v_pk_fma_f32 v[88:89], v[74:75], v[80:81], v[88:89] op_sel:[0,0,0] op_sel_hi:[0,1,1]
	v_pk_fma_f32 v[90:91], v[74:75], v[80:81], v[90:91] op_sel:[1,0,0] op_sel_hi:[1,1,1]
	v_mov_b32_dpp v58, v59 quad_perm:[0,1,2,3] row_mask:0xf bank_mask:0xa
	v_pk_fma_f32 v[2:3], v[68:69], v[22:23], v[84:85] op_sel:[0,0,0] op_sel_hi:[0,1,1] neg_lo:[1,0,0] neg_hi:[1,0,0]
	v_pk_fma_f32 v[4:5], v[68:69], v[22:23], v[86:87] op_sel:[1,0,0] op_sel_hi:[1,1,1] neg_lo:[1,0,0] neg_hi:[1,0,0]
	v_pk_fma_f32 v[6:7], v[70:71], v[22:23], v[88:89] op_sel:[0,0,0] op_sel_hi:[0,1,1] neg_lo:[1,0,0] neg_hi:[1,0,0]
	v_pk_fma_f32 v[8:9], v[70:71], v[22:23], v[90:91] op_sel:[1,0,0] op_sel_hi:[1,1,1] neg_lo:[1,0,0] neg_hi:[1,0,0]
	s_waitcnt lgkmcnt(0)
	ds_read_b128 v[60:63], v20 offset:3840
	ds_read_b128 v[64:67], v20 offset:12032
	ds_read_b64 v[80:81], v21 offset:44800
	ds_read_b128 v[72:75], v20 offset:28416
	ds_read_b128 v[68:71], v20 offset:20224
	ds_read_b128 v[52:55], v20 offset:36608
	v_pk_mul_f32 v[22:23], v[2:3], v[36:37] op_sel:[0,0] op_sel_hi:[1,0]
	v_pk_mul_f32 v[26:27], v[2:3], v[76:77] op_sel:[0,0] op_sel_hi:[1,0]
	v_pk_fma_f32 v[22:23], v[4:5], v[36:37], v[22:23] op_sel:[0,1,0] op_sel_hi:[1,1,1]
	v_pk_fma_f32 v[26:27], v[4:5], v[76:77], v[26:27] op_sel:[0,1,0] op_sel_hi:[1,1,1]
	v_pk_fma_f32 v[22:23], v[6:7], v[38:39], v[22:23] op_sel:[0,0,0] op_sel_hi:[1,0,1]
	v_pk_fma_f32 v[26:27], v[6:7], v[78:79], v[26:27] op_sel:[0,0,0] op_sel_hi:[1,0,1]
	v_pk_fma_f32 v[22:23], v[8:9], v[38:39], v[22:23] op_sel:[0,1,0] op_sel_hi:[1,1,1]
	v_pk_fma_f32 v[26:27], v[8:9], v[78:79], v[26:27] op_sel:[0,1,0] op_sel_hi:[1,1,1]
	v_add_f32_dpp v28, v28, v28 row_ror:8 row_mask:0xf bank_mask:0x3
	v_add_f32_dpp v58, v58, v58 row_ror:8 row_mask:0xf bank_mask:0xc
	v_add_f32_dpp v22, v22, v22 quad_perm:[1,0,3,2] row_mask:0xf bank_mask:0xf
	v_add_f32_dpp v23, v23, v23 quad_perm:[1,0,3,2] row_mask:0xf bank_mask:0xf
	v_pk_mul_f32 v[84:85], v[2:3], v[40:41] op_sel:[0,0] op_sel_hi:[1,0]
	v_pk_mul_f32 v[86:87], v[4:5], v[40:41] op_sel:[0,1] op_sel_hi:[1,1]
	v_mov_b32_dpp v28, v58 quad_perm:[0,1,2,3] row_mask:0xf bank_mask:0xc
	v_add_f32_dpp v22, v22, v22 quad_perm:[2,3,0,1] row_mask:0xf bank_mask:0xf
	v_add_f32_dpp v23, v23, v23 quad_perm:[2,3,0,1] row_mask:0xf bank_mask:0xf
	v_pk_mul_f32 v[88:89], v[6:7], v[42:43] op_sel:[0,0] op_sel_hi:[1,0]
	v_pk_mul_f32 v[90:91], v[8:9], v[42:43] op_sel:[0,1] op_sel_hi:[1,1]
	v_add_f32_dpp v28, v28, v28 quad_perm:[1,0,3,2] row_mask:0xf bank_mask:0xf
	v_add_f32_dpp v22, v22, v22 row_half_mirror row_mask:0xf bank_mask:0xf
	v_add_f32_dpp v23, v23, v23 row_half_mirror row_mask:0xf bank_mask:0xf
	v_pk_fma_f32 v[84:85], v[48:49], v[56:57], v[84:85] op_sel:[0,0,0] op_sel_hi:[0,1,1]
	v_pk_fma_f32 v[86:87], v[48:49], v[56:57], v[86:87] op_sel:[1,0,0] op_sel_hi:[1,1,1]
	v_add_f32_dpp v28, v28, v28 quad_perm:[2,3,0,1] row_mask:0xf bank_mask:0xf
	v_add_f32_dpp v22, v22, v22 row_mirror row_mask:0xf bank_mask:0xf
	v_add_f32_dpp v23, v23, v23 row_mirror row_mask:0xf bank_mask:0xf
	v_pk_fma_f32 v[88:89], v[50:51], v[56:57], v[88:89] op_sel:[0,0,0] op_sel_hi:[0,1,1]
	v_pk_fma_f32 v[90:91], v[50:51], v[56:57], v[90:91] op_sel:[1,0,0] op_sel_hi:[1,1,1]
	v_cndmask_b32_e64 v31, v31, v28, s[6:7]
	v_pk_fma_f32 v[2:3], v[44:45], v[22:23], v[84:85] op_sel:[0,0,0] op_sel_hi:[0,1,1] neg_lo:[1,0,0] neg_hi:[1,0,0]
	v_pk_fma_f32 v[4:5], v[44:45], v[22:23], v[86:87] op_sel:[1,0,0] op_sel_hi:[1,1,1] neg_lo:[1,0,0] neg_hi:[1,0,0]
	v_pk_fma_f32 v[6:7], v[46:47], v[22:23], v[88:89] op_sel:[0,0,0] op_sel_hi:[0,1,1] neg_lo:[1,0,0] neg_hi:[1,0,0]
	v_pk_fma_f32 v[8:9], v[46:47], v[22:23], v[90:91] op_sel:[1,0,0] op_sel_hi:[1,1,1] neg_lo:[1,0,0] neg_hi:[1,0,0]
	s_waitcnt lgkmcnt(0)
	ds_read_b128 v[36:39], v20 offset:4096
	ds_read_b128 v[40:43], v20 offset:12288
	ds_read_b64 v[56:57], v21 offset:45056
	ds_read_b128 v[48:51], v20 offset:28672
	ds_read_b128 v[44:47], v20 offset:20480
	ds_read_b128 v[76:79], v20 offset:36864
	v_pk_mul_f32 v[22:23], v[2:3], v[60:61] op_sel:[0,0] op_sel_hi:[1,0]
	v_pk_mul_f32 v[28:29], v[2:3], v[92:93] op_sel:[0,0] op_sel_hi:[1,0]
	v_pk_fma_f32 v[22:23], v[4:5], v[60:61], v[22:23] op_sel:[0,1,0] op_sel_hi:[1,1,1]
	v_pk_fma_f32 v[28:29], v[4:5], v[92:93], v[28:29] op_sel:[0,1,0] op_sel_hi:[1,1,1]
	v_pk_fma_f32 v[22:23], v[6:7], v[62:63], v[22:23] op_sel:[0,0,0] op_sel_hi:[1,0,1]
	v_pk_fma_f32 v[28:29], v[6:7], v[94:95], v[28:29] op_sel:[0,0,0] op_sel_hi:[1,0,1]
	v_pk_fma_f32 v[22:23], v[8:9], v[62:63], v[22:23] op_sel:[0,1,0] op_sel_hi:[1,1,1]
	v_pk_fma_f32 v[28:29], v[8:9], v[94:95], v[28:29] op_sel:[0,1,0] op_sel_hi:[1,1,1]
	v_add_f32_dpp v24, v24, v24 row_ror:12 row_mask:0xf bank_mask:0x5
	v_add_f32_dpp v25, v25, v25 row_ror:4 row_mask:0xf bank_mask:0xa
	v_add_f32_dpp v22, v22, v22 quad_perm:[1,0,3,2] row_mask:0xf bank_mask:0xf
	v_add_f32_dpp v23, v23, v23 quad_perm:[1,0,3,2] row_mask:0xf bank_mask:0xf
	v_pk_mul_f32 v[84:85], v[2:3], v[64:65] op_sel:[0,0] op_sel_hi:[1,0]
	v_pk_mul_f32 v[86:87], v[4:5], v[64:65] op_sel:[0,1] op_sel_hi:[1,1]
	v_add_f32_dpp v26, v26, v26 row_ror:12 row_mask:0xf bank_mask:0x5
	v_add_f32_dpp v22, v22, v22 quad_perm:[2,3,0,1] row_mask:0xf bank_mask:0xf
	v_add_f32_dpp v23, v23, v23 quad_perm:[2,3,0,1] row_mask:0xf bank_mask:0xf
	v_pk_mul_f32 v[88:89], v[6:7], v[66:67] op_sel:[0,0] op_sel_hi:[1,0]
	v_pk_mul_f32 v[90:91], v[8:9], v[66:67] op_sel:[0,1] op_sel_hi:[1,1]
	v_add_f32_dpp v27, v27, v27 row_ror:4 row_mask:0xf bank_mask:0xa
	v_add_f32_dpp v22, v22, v22 row_half_mirror row_mask:0xf bank_mask:0xf
	v_add_f32_dpp v23, v23, v23 row_half_mirror row_mask:0xf bank_mask:0xf
	v_pk_fma_f32 v[84:85], v[72:73], v[80:81], v[84:85] op_sel:[0,0,0] op_sel_hi:[0,1,1]
	v_pk_fma_f32 v[86:87], v[72:73], v[80:81], v[86:87] op_sel:[1,0,0] op_sel_hi:[1,1,1]
	v_mov_b32_dpp v24, v25 quad_perm:[0,1,2,3] row_mask:0xf bank_mask:0xa
	v_add_f32_dpp v22, v22, v22 row_mirror row_mask:0xf bank_mask:0xf
	v_add_f32_dpp v23, v23, v23 row_mirror row_mask:0xf bank_mask:0xf
	v_pk_fma_f32 v[88:89], v[74:75], v[80:81], v[88:89] op_sel:[0,0,0] op_sel_hi:[0,1,1]
	v_pk_fma_f32 v[90:91], v[74:75], v[80:81], v[90:91] op_sel:[1,0,0] op_sel_hi:[1,1,1]
	v_mov_b32_dpp v26, v27 quad_perm:[0,1,2,3] row_mask:0xf bank_mask:0xa
	v_pk_fma_f32 v[2:3], v[68:69], v[22:23], v[84:85] op_sel:[0,0,0] op_sel_hi:[0,1,1] neg_lo:[1,0,0] neg_hi:[1,0,0]
	v_pk_fma_f32 v[4:5], v[68:69], v[22:23], v[86:87] op_sel:[1,0,0] op_sel_hi:[1,1,1] neg_lo:[1,0,0] neg_hi:[1,0,0]
	v_pk_fma_f32 v[6:7], v[70:71], v[22:23], v[88:89] op_sel:[0,0,0] op_sel_hi:[0,1,1] neg_lo:[1,0,0] neg_hi:[1,0,0]
	v_pk_fma_f32 v[8:9], v[70:71], v[22:23], v[90:91] op_sel:[1,0,0] op_sel_hi:[1,1,1] neg_lo:[1,0,0] neg_hi:[1,0,0]
	s_waitcnt lgkmcnt(0)
	ds_read_b128 v[60:63], v20 offset:4352
	ds_read_b128 v[64:67], v20 offset:12544
	ds_read_b64 v[80:81], v21 offset:45312
	ds_read_b128 v[72:75], v20 offset:28928
	ds_read_b128 v[68:71], v20 offset:20736
	ds_read_b128 v[92:95], v20 offset:37120
	v_pk_mul_f32 v[22:23], v[2:3], v[36:37] op_sel:[0,0] op_sel_hi:[1,0]
	v_pk_mul_f32 v[58:59], v[2:3], v[52:53] op_sel:[0,0] op_sel_hi:[1,0]
	v_pk_fma_f32 v[22:23], v[4:5], v[36:37], v[22:23] op_sel:[0,1,0] op_sel_hi:[1,1,1]
	v_pk_fma_f32 v[58:59], v[4:5], v[52:53], v[58:59] op_sel:[0,1,0] op_sel_hi:[1,1,1]
	v_pk_fma_f32 v[22:23], v[6:7], v[38:39], v[22:23] op_sel:[0,0,0] op_sel_hi:[1,0,1]
	v_pk_fma_f32 v[58:59], v[6:7], v[54:55], v[58:59] op_sel:[0,0,0] op_sel_hi:[1,0,1]
	v_pk_fma_f32 v[22:23], v[8:9], v[38:39], v[22:23] op_sel:[0,1,0] op_sel_hi:[1,1,1]
	v_pk_fma_f32 v[58:59], v[8:9], v[54:55], v[58:59] op_sel:[0,1,0] op_sel_hi:[1,1,1]
	v_add_f32_dpp v24, v24, v24 row_ror:8 row_mask:0xf bank_mask:0x3
	v_add_f32_dpp v26, v26, v26 row_ror:8 row_mask:0xf bank_mask:0xc
	v_add_f32_dpp v22, v22, v22 quad_perm:[1,0,3,2] row_mask:0xf bank_mask:0xf
	v_add_f32_dpp v23, v23, v23 quad_perm:[1,0,3,2] row_mask:0xf bank_mask:0xf
	v_pk_mul_f32 v[84:85], v[2:3], v[40:41] op_sel:[0,0] op_sel_hi:[1,0]
	v_pk_mul_f32 v[86:87], v[4:5], v[40:41] op_sel:[0,1] op_sel_hi:[1,1]
	v_mov_b32_dpp v24, v26 quad_perm:[0,1,2,3] row_mask:0xf bank_mask:0xc
	v_add_f32_dpp v22, v22, v22 quad_perm:[2,3,0,1] row_mask:0xf bank_mask:0xf
	v_add_f32_dpp v23, v23, v23 quad_perm:[2,3,0,1] row_mask:0xf bank_mask:0xf
	v_pk_mul_f32 v[88:89], v[6:7], v[42:43] op_sel:[0,0] op_sel_hi:[1,0]
	v_pk_mul_f32 v[90:91], v[8:9], v[42:43] op_sel:[0,1] op_sel_hi:[1,1]
	v_add_f32_dpp v24, v24, v24 quad_perm:[1,0,3,2] row_mask:0xf bank_mask:0xf
	v_add_f32_dpp v22, v22, v22 row_half_mirror row_mask:0xf bank_mask:0xf
	v_add_f32_dpp v23, v23, v23 row_half_mirror row_mask:0xf bank_mask:0xf
	v_pk_fma_f32 v[84:85], v[48:49], v[56:57], v[84:85] op_sel:[0,0,0] op_sel_hi:[0,1,1]
	v_pk_fma_f32 v[86:87], v[48:49], v[56:57], v[86:87] op_sel:[1,0,0] op_sel_hi:[1,1,1]
	v_add_f32_dpp v24, v24, v24 quad_perm:[2,3,0,1] row_mask:0xf bank_mask:0xf
	v_add_f32_dpp v22, v22, v22 row_mirror row_mask:0xf bank_mask:0xf
	v_add_f32_dpp v23, v23, v23 row_mirror row_mask:0xf bank_mask:0xf
	v_pk_fma_f32 v[88:89], v[50:51], v[56:57], v[88:89] op_sel:[0,0,0] op_sel_hi:[0,1,1]
	v_pk_fma_f32 v[90:91], v[50:51], v[56:57], v[90:91] op_sel:[1,0,0] op_sel_hi:[1,1,1]
	v_cndmask_b32_e64 v31, v31, v24, s[8:9]
	v_pk_fma_f32 v[2:3], v[44:45], v[22:23], v[84:85] op_sel:[0,0,0] op_sel_hi:[0,1,1] neg_lo:[1,0,0] neg_hi:[1,0,0]
	v_pk_fma_f32 v[4:5], v[44:45], v[22:23], v[86:87] op_sel:[1,0,0] op_sel_hi:[1,1,1] neg_lo:[1,0,0] neg_hi:[1,0,0]
	v_pk_fma_f32 v[6:7], v[46:47], v[22:23], v[88:89] op_sel:[0,0,0] op_sel_hi:[0,1,1] neg_lo:[1,0,0] neg_hi:[1,0,0]
	v_pk_fma_f32 v[8:9], v[46:47], v[22:23], v[90:91] op_sel:[1,0,0] op_sel_hi:[1,1,1] neg_lo:[1,0,0] neg_hi:[1,0,0]
	s_waitcnt lgkmcnt(0)
	ds_read_b128 v[36:39], v20 offset:4608
	ds_read_b128 v[40:43], v20 offset:12800
	ds_read_b64 v[56:57], v21 offset:45568
	ds_read_b128 v[48:51], v20 offset:29184
	ds_read_b128 v[44:47], v20 offset:20992
	ds_read_b128 v[52:55], v20 offset:37376
	v_pk_mul_f32 v[22:23], v[2:3], v[60:61] op_sel:[0,0] op_sel_hi:[1,0]
	v_pk_mul_f32 v[24:25], v[2:3], v[76:77] op_sel:[0,0] op_sel_hi:[1,0]
	v_pk_fma_f32 v[22:23], v[4:5], v[60:61], v[22:23] op_sel:[0,1,0] op_sel_hi:[1,1,1]
	v_pk_fma_f32 v[24:25], v[4:5], v[76:77], v[24:25] op_sel:[0,1,0] op_sel_hi:[1,1,1]
	v_pk_fma_f32 v[22:23], v[6:7], v[62:63], v[22:23] op_sel:[0,0,0] op_sel_hi:[1,0,1]
	v_pk_fma_f32 v[24:25], v[6:7], v[78:79], v[24:25] op_sel:[0,0,0] op_sel_hi:[1,0,1]
	v_pk_fma_f32 v[22:23], v[8:9], v[62:63], v[22:23] op_sel:[0,1,0] op_sel_hi:[1,1,1]
	v_pk_fma_f32 v[24:25], v[8:9], v[78:79], v[24:25] op_sel:[0,1,0] op_sel_hi:[1,1,1]
	v_add_f32_dpp v28, v28, v28 row_ror:12 row_mask:0xf bank_mask:0x5
	v_add_f32_dpp v29, v29, v29 row_ror:4 row_mask:0xf bank_mask:0xa
	v_add_f32_dpp v22, v22, v22 quad_perm:[1,0,3,2] row_mask:0xf bank_mask:0xf
	v_add_f32_dpp v23, v23, v23 quad_perm:[1,0,3,2] row_mask:0xf bank_mask:0xf
	v_pk_mul_f32 v[84:85], v[2:3], v[64:65] op_sel:[0,0] op_sel_hi:[1,0]
	v_pk_mul_f32 v[86:87], v[4:5], v[64:65] op_sel:[0,1] op_sel_hi:[1,1]
	v_add_f32_dpp v58, v58, v58 row_ror:12 row_mask:0xf bank_mask:0x5
	v_add_f32_dpp v22, v22, v22 quad_perm:[2,3,0,1] row_mask:0xf bank_mask:0xf
	v_add_f32_dpp v23, v23, v23 quad_perm:[2,3,0,1] row_mask:0xf bank_mask:0xf
	v_pk_mul_f32 v[88:89], v[6:7], v[66:67] op_sel:[0,0] op_sel_hi:[1,0]
	v_pk_mul_f32 v[90:91], v[8:9], v[66:67] op_sel:[0,1] op_sel_hi:[1,1]
	v_add_f32_dpp v59, v59, v59 row_ror:4 row_mask:0xf bank_mask:0xa
	v_add_f32_dpp v22, v22, v22 row_half_mirror row_mask:0xf bank_mask:0xf
	v_add_f32_dpp v23, v23, v23 row_half_mirror row_mask:0xf bank_mask:0xf
	v_pk_fma_f32 v[84:85], v[72:73], v[80:81], v[84:85] op_sel:[0,0,0] op_sel_hi:[0,1,1]
	v_pk_fma_f32 v[86:87], v[72:73], v[80:81], v[86:87] op_sel:[1,0,0] op_sel_hi:[1,1,1]
	v_mov_b32_dpp v28, v29 quad_perm:[0,1,2,3] row_mask:0xf bank_mask:0xa
	v_add_f32_dpp v22, v22, v22 row_mirror row_mask:0xf bank_mask:0xf
	v_add_f32_dpp v23, v23, v23 row_mirror row_mask:0xf bank_mask:0xf
	v_pk_fma_f32 v[88:89], v[74:75], v[80:81], v[88:89] op_sel:[0,0,0] op_sel_hi:[0,1,1]
	v_pk_fma_f32 v[90:91], v[74:75], v[80:81], v[90:91] op_sel:[1,0,0] op_sel_hi:[1,1,1]
	v_mov_b32_dpp v58, v59 quad_perm:[0,1,2,3] row_mask:0xf bank_mask:0xa
	v_pk_fma_f32 v[2:3], v[68:69], v[22:23], v[84:85] op_sel:[0,0,0] op_sel_hi:[0,1,1] neg_lo:[1,0,0] neg_hi:[1,0,0]
	v_pk_fma_f32 v[4:5], v[68:69], v[22:23], v[86:87] op_sel:[1,0,0] op_sel_hi:[1,1,1] neg_lo:[1,0,0] neg_hi:[1,0,0]
	v_pk_fma_f32 v[6:7], v[70:71], v[22:23], v[88:89] op_sel:[0,0,0] op_sel_hi:[0,1,1] neg_lo:[1,0,0] neg_hi:[1,0,0]
	v_pk_fma_f32 v[8:9], v[70:71], v[22:23], v[90:91] op_sel:[1,0,0] op_sel_hi:[1,1,1] neg_lo:[1,0,0] neg_hi:[1,0,0]
	s_waitcnt lgkmcnt(0)
	ds_read_b128 v[60:63], v20 offset:4864
	ds_read_b128 v[64:67], v20 offset:13056
	ds_read_b64 v[80:81], v21 offset:45824
	ds_read_b128 v[72:75], v20 offset:29440
	ds_read_b128 v[68:71], v20 offset:21248
	ds_read_b128 v[76:79], v20 offset:37632
	v_pk_mul_f32 v[22:23], v[2:3], v[36:37] op_sel:[0,0] op_sel_hi:[1,0]
	v_pk_mul_f32 v[26:27], v[2:3], v[92:93] op_sel:[0,0] op_sel_hi:[1,0]
	v_pk_fma_f32 v[22:23], v[4:5], v[36:37], v[22:23] op_sel:[0,1,0] op_sel_hi:[1,1,1]
	v_pk_fma_f32 v[26:27], v[4:5], v[92:93], v[26:27] op_sel:[0,1,0] op_sel_hi:[1,1,1]
	v_pk_fma_f32 v[22:23], v[6:7], v[38:39], v[22:23] op_sel:[0,0,0] op_sel_hi:[1,0,1]
	v_pk_fma_f32 v[26:27], v[6:7], v[94:95], v[26:27] op_sel:[0,0,0] op_sel_hi:[1,0,1]
	v_pk_fma_f32 v[22:23], v[8:9], v[38:39], v[22:23] op_sel:[0,1,0] op_sel_hi:[1,1,1]
	v_pk_fma_f32 v[26:27], v[8:9], v[94:95], v[26:27] op_sel:[0,1,0] op_sel_hi:[1,1,1]
	v_add_f32_dpp v28, v28, v28 row_ror:8 row_mask:0xf bank_mask:0x3
	v_add_f32_dpp v58, v58, v58 row_ror:8 row_mask:0xf bank_mask:0xc
	v_add_f32_dpp v22, v22, v22 quad_perm:[1,0,3,2] row_mask:0xf bank_mask:0xf
	v_add_f32_dpp v23, v23, v23 quad_perm:[1,0,3,2] row_mask:0xf bank_mask:0xf
	v_pk_mul_f32 v[84:85], v[2:3], v[40:41] op_sel:[0,0] op_sel_hi:[1,0]
	v_pk_mul_f32 v[86:87], v[4:5], v[40:41] op_sel:[0,1] op_sel_hi:[1,1]
	v_mov_b32_dpp v28, v58 quad_perm:[0,1,2,3] row_mask:0xf bank_mask:0xc
	v_add_f32_dpp v22, v22, v22 quad_perm:[2,3,0,1] row_mask:0xf bank_mask:0xf
	v_add_f32_dpp v23, v23, v23 quad_perm:[2,3,0,1] row_mask:0xf bank_mask:0xf
	v_pk_mul_f32 v[88:89], v[6:7], v[42:43] op_sel:[0,0] op_sel_hi:[1,0]
	v_pk_mul_f32 v[90:91], v[8:9], v[42:43] op_sel:[0,1] op_sel_hi:[1,1]
	v_add_f32_dpp v28, v28, v28 quad_perm:[1,0,3,2] row_mask:0xf bank_mask:0xf
	v_add_f32_dpp v22, v22, v22 row_half_mirror row_mask:0xf bank_mask:0xf
	v_add_f32_dpp v23, v23, v23 row_half_mirror row_mask:0xf bank_mask:0xf
	v_pk_fma_f32 v[84:85], v[48:49], v[56:57], v[84:85] op_sel:[0,0,0] op_sel_hi:[0,1,1]
	v_pk_fma_f32 v[86:87], v[48:49], v[56:57], v[86:87] op_sel:[1,0,0] op_sel_hi:[1,1,1]
	v_add_f32_dpp v28, v28, v28 quad_perm:[2,3,0,1] row_mask:0xf bank_mask:0xf
	v_add_f32_dpp v22, v22, v22 row_mirror row_mask:0xf bank_mask:0xf
	v_add_f32_dpp v23, v23, v23 row_mirror row_mask:0xf bank_mask:0xf
	v_pk_fma_f32 v[88:89], v[50:51], v[56:57], v[88:89] op_sel:[0,0,0] op_sel_hi:[0,1,1]
	v_pk_fma_f32 v[90:91], v[50:51], v[56:57], v[90:91] op_sel:[1,0,0] op_sel_hi:[1,1,1]
	v_cndmask_b32_e64 v31, v31, v28, s[10:11]
	v_pk_fma_f32 v[2:3], v[44:45], v[22:23], v[84:85] op_sel:[0,0,0] op_sel_hi:[0,1,1] neg_lo:[1,0,0] neg_hi:[1,0,0]
	v_pk_fma_f32 v[4:5], v[44:45], v[22:23], v[86:87] op_sel:[1,0,0] op_sel_hi:[1,1,1] neg_lo:[1,0,0] neg_hi:[1,0,0]
	v_pk_fma_f32 v[6:7], v[46:47], v[22:23], v[88:89] op_sel:[0,0,0] op_sel_hi:[0,1,1] neg_lo:[1,0,0] neg_hi:[1,0,0]
	v_pk_fma_f32 v[8:9], v[46:47], v[22:23], v[90:91] op_sel:[1,0,0] op_sel_hi:[1,1,1] neg_lo:[1,0,0] neg_hi:[1,0,0]
	s_waitcnt lgkmcnt(0)
	ds_read_b128 v[36:39], v20 offset:5120
	ds_read_b128 v[40:43], v20 offset:13312
	ds_read_b64 v[56:57], v21 offset:46080
	ds_read_b128 v[48:51], v20 offset:29696
	ds_read_b128 v[44:47], v20 offset:21504
	ds_read_b128 v[92:95], v20 offset:37888
	v_pk_mul_f32 v[22:23], v[2:3], v[60:61] op_sel:[0,0] op_sel_hi:[1,0]
	v_pk_mul_f32 v[28:29], v[2:3], v[52:53] op_sel:[0,0] op_sel_hi:[1,0]
	v_pk_fma_f32 v[22:23], v[4:5], v[60:61], v[22:23] op_sel:[0,1,0] op_sel_hi:[1,1,1]
	v_pk_fma_f32 v[28:29], v[4:5], v[52:53], v[28:29] op_sel:[0,1,0] op_sel_hi:[1,1,1]
	v_pk_fma_f32 v[22:23], v[6:7], v[62:63], v[22:23] op_sel:[0,0,0] op_sel_hi:[1,0,1]
	v_pk_fma_f32 v[28:29], v[6:7], v[54:55], v[28:29] op_sel:[0,0,0] op_sel_hi:[1,0,1]
	v_pk_fma_f32 v[22:23], v[8:9], v[62:63], v[22:23] op_sel:[0,1,0] op_sel_hi:[1,1,1]
	v_pk_fma_f32 v[28:29], v[8:9], v[54:55], v[28:29] op_sel:[0,1,0] op_sel_hi:[1,1,1]
	v_add_f32_dpp v24, v24, v24 row_ror:12 row_mask:0xf bank_mask:0x5
	v_add_f32_dpp v25, v25, v25 row_ror:4 row_mask:0xf bank_mask:0xa
	v_add_f32_dpp v22, v22, v22 quad_perm:[1,0,3,2] row_mask:0xf bank_mask:0xf
	v_add_f32_dpp v23, v23, v23 quad_perm:[1,0,3,2] row_mask:0xf bank_mask:0xf
	v_pk_mul_f32 v[84:85], v[2:3], v[64:65] op_sel:[0,0] op_sel_hi:[1,0]
	v_pk_mul_f32 v[86:87], v[4:5], v[64:65] op_sel:[0,1] op_sel_hi:[1,1]
	v_add_f32_dpp v26, v26, v26 row_ror:12 row_mask:0xf bank_mask:0x5
	v_add_f32_dpp v22, v22, v22 quad_perm:[2,3,0,1] row_mask:0xf bank_mask:0xf
	v_add_f32_dpp v23, v23, v23 quad_perm:[2,3,0,1] row_mask:0xf bank_mask:0xf
	v_pk_mul_f32 v[88:89], v[6:7], v[66:67] op_sel:[0,0] op_sel_hi:[1,0]
	v_pk_mul_f32 v[90:91], v[8:9], v[66:67] op_sel:[0,1] op_sel_hi:[1,1]
	v_add_f32_dpp v27, v27, v27 row_ror:4 row_mask:0xf bank_mask:0xa
	v_add_f32_dpp v22, v22, v22 row_half_mirror row_mask:0xf bank_mask:0xf
	v_add_f32_dpp v23, v23, v23 row_half_mirror row_mask:0xf bank_mask:0xf
	v_pk_fma_f32 v[84:85], v[72:73], v[80:81], v[84:85] op_sel:[0,0,0] op_sel_hi:[0,1,1]
	v_pk_fma_f32 v[86:87], v[72:73], v[80:81], v[86:87] op_sel:[1,0,0] op_sel_hi:[1,1,1]
	v_mov_b32_dpp v24, v25 quad_perm:[0,1,2,3] row_mask:0xf bank_mask:0xa
	v_add_f32_dpp v22, v22, v22 row_mirror row_mask:0xf bank_mask:0xf
	v_add_f32_dpp v23, v23, v23 row_mirror row_mask:0xf bank_mask:0xf
	v_pk_fma_f32 v[88:89], v[74:75], v[80:81], v[88:89] op_sel:[0,0,0] op_sel_hi:[0,1,1]
	v_pk_fma_f32 v[90:91], v[74:75], v[80:81], v[90:91] op_sel:[1,0,0] op_sel_hi:[1,1,1]
	v_mov_b32_dpp v26, v27 quad_perm:[0,1,2,3] row_mask:0xf bank_mask:0xa
	v_pk_fma_f32 v[2:3], v[68:69], v[22:23], v[84:85] op_sel:[0,0,0] op_sel_hi:[0,1,1] neg_lo:[1,0,0] neg_hi:[1,0,0]
	v_pk_fma_f32 v[4:5], v[68:69], v[22:23], v[86:87] op_sel:[1,0,0] op_sel_hi:[1,1,1] neg_lo:[1,0,0] neg_hi:[1,0,0]
	v_pk_fma_f32 v[6:7], v[70:71], v[22:23], v[88:89] op_sel:[0,0,0] op_sel_hi:[0,1,1] neg_lo:[1,0,0] neg_hi:[1,0,0]
	v_pk_fma_f32 v[8:9], v[70:71], v[22:23], v[90:91] op_sel:[1,0,0] op_sel_hi:[1,1,1] neg_lo:[1,0,0] neg_hi:[1,0,0]
	s_waitcnt lgkmcnt(0)
	ds_read_b128 v[60:63], v20 offset:5376
	ds_read_b128 v[64:67], v20 offset:13568
	ds_read_b64 v[80:81], v21 offset:46336
	ds_read_b128 v[72:75], v20 offset:29952
	ds_read_b128 v[68:71], v20 offset:21760
	ds_read_b128 v[52:55], v20 offset:38144
	v_pk_mul_f32 v[22:23], v[2:3], v[36:37] op_sel:[0,0] op_sel_hi:[1,0]
	v_pk_mul_f32 v[58:59], v[2:3], v[76:77] op_sel:[0,0] op_sel_hi:[1,0]
	v_pk_fma_f32 v[22:23], v[4:5], v[36:37], v[22:23] op_sel:[0,1,0] op_sel_hi:[1,1,1]
	v_pk_fma_f32 v[58:59], v[4:5], v[76:77], v[58:59] op_sel:[0,1,0] op_sel_hi:[1,1,1]
	v_pk_fma_f32 v[22:23], v[6:7], v[38:39], v[22:23] op_sel:[0,0,0] op_sel_hi:[1,0,1]
	v_pk_fma_f32 v[58:59], v[6:7], v[78:79], v[58:59] op_sel:[0,0,0] op_sel_hi:[1,0,1]
	v_pk_fma_f32 v[22:23], v[8:9], v[38:39], v[22:23] op_sel:[0,1,0] op_sel_hi:[1,1,1]
	v_pk_fma_f32 v[58:59], v[8:9], v[78:79], v[58:59] op_sel:[0,1,0] op_sel_hi:[1,1,1]
	v_add_f32_dpp v24, v24, v24 row_ror:8 row_mask:0xf bank_mask:0x3
	v_add_f32_dpp v26, v26, v26 row_ror:8 row_mask:0xf bank_mask:0xc
	v_add_f32_dpp v22, v22, v22 quad_perm:[1,0,3,2] row_mask:0xf bank_mask:0xf
	v_add_f32_dpp v23, v23, v23 quad_perm:[1,0,3,2] row_mask:0xf bank_mask:0xf
	v_pk_mul_f32 v[84:85], v[2:3], v[40:41] op_sel:[0,0] op_sel_hi:[1,0]
	v_pk_mul_f32 v[86:87], v[4:5], v[40:41] op_sel:[0,1] op_sel_hi:[1,1]
	v_mov_b32_dpp v24, v26 quad_perm:[0,1,2,3] row_mask:0xf bank_mask:0xc
	v_add_f32_dpp v22, v22, v22 quad_perm:[2,3,0,1] row_mask:0xf bank_mask:0xf
	v_add_f32_dpp v23, v23, v23 quad_perm:[2,3,0,1] row_mask:0xf bank_mask:0xf
	v_pk_mul_f32 v[88:89], v[6:7], v[42:43] op_sel:[0,0] op_sel_hi:[1,0]
	v_pk_mul_f32 v[90:91], v[8:9], v[42:43] op_sel:[0,1] op_sel_hi:[1,1]
	v_add_f32_dpp v24, v24, v24 quad_perm:[1,0,3,2] row_mask:0xf bank_mask:0xf
	v_add_f32_dpp v22, v22, v22 row_half_mirror row_mask:0xf bank_mask:0xf
	v_add_f32_dpp v23, v23, v23 row_half_mirror row_mask:0xf bank_mask:0xf
	v_pk_fma_f32 v[84:85], v[48:49], v[56:57], v[84:85] op_sel:[0,0,0] op_sel_hi:[0,1,1]
	v_pk_fma_f32 v[86:87], v[48:49], v[56:57], v[86:87] op_sel:[1,0,0] op_sel_hi:[1,1,1]
	v_add_f32_dpp v24, v24, v24 quad_perm:[2,3,0,1] row_mask:0xf bank_mask:0xf
	v_add_f32_dpp v22, v22, v22 row_mirror row_mask:0xf bank_mask:0xf
	v_add_f32_dpp v23, v23, v23 row_mirror row_mask:0xf bank_mask:0xf
	v_pk_fma_f32 v[88:89], v[50:51], v[56:57], v[88:89] op_sel:[0,0,0] op_sel_hi:[0,1,1]
	v_pk_fma_f32 v[90:91], v[50:51], v[56:57], v[90:91] op_sel:[1,0,0] op_sel_hi:[1,1,1]
	v_cndmask_b32_e64 v32, 0, v24, s[0:1]
	v_pk_fma_f32 v[2:3], v[44:45], v[22:23], v[84:85] op_sel:[0,0,0] op_sel_hi:[0,1,1] neg_lo:[1,0,0] neg_hi:[1,0,0]
	v_pk_fma_f32 v[4:5], v[44:45], v[22:23], v[86:87] op_sel:[1,0,0] op_sel_hi:[1,1,1] neg_lo:[1,0,0] neg_hi:[1,0,0]
	v_pk_fma_f32 v[6:7], v[46:47], v[22:23], v[88:89] op_sel:[0,0,0] op_sel_hi:[0,1,1] neg_lo:[1,0,0] neg_hi:[1,0,0]
	v_pk_fma_f32 v[8:9], v[46:47], v[22:23], v[90:91] op_sel:[1,0,0] op_sel_hi:[1,1,1] neg_lo:[1,0,0] neg_hi:[1,0,0]
	s_waitcnt lgkmcnt(0)
	ds_read_b128 v[36:39], v20 offset:5632
	ds_read_b128 v[40:43], v20 offset:13824
	ds_read_b64 v[56:57], v21 offset:46592
	ds_read_b128 v[48:51], v20 offset:30208
	ds_read_b128 v[44:47], v20 offset:22016
	ds_read_b128 v[76:79], v20 offset:38400
	v_pk_mul_f32 v[22:23], v[2:3], v[60:61] op_sel:[0,0] op_sel_hi:[1,0]
	v_pk_mul_f32 v[24:25], v[2:3], v[92:93] op_sel:[0,0] op_sel_hi:[1,0]
	v_pk_fma_f32 v[22:23], v[4:5], v[60:61], v[22:23] op_sel:[0,1,0] op_sel_hi:[1,1,1]
	v_pk_fma_f32 v[24:25], v[4:5], v[92:93], v[24:25] op_sel:[0,1,0] op_sel_hi:[1,1,1]
	v_pk_fma_f32 v[22:23], v[6:7], v[62:63], v[22:23] op_sel:[0,0,0] op_sel_hi:[1,0,1]
	v_pk_fma_f32 v[24:25], v[6:7], v[94:95], v[24:25] op_sel:[0,0,0] op_sel_hi:[1,0,1]
	v_pk_fma_f32 v[22:23], v[8:9], v[62:63], v[22:23] op_sel:[0,1,0] op_sel_hi:[1,1,1]
	v_pk_fma_f32 v[24:25], v[8:9], v[94:95], v[24:25] op_sel:[0,1,0] op_sel_hi:[1,1,1]
	v_add_f32_dpp v28, v28, v28 row_ror:12 row_mask:0xf bank_mask:0x5
	v_add_f32_dpp v29, v29, v29 row_ror:4 row_mask:0xf bank_mask:0xa
	v_add_f32_dpp v22, v22, v22 quad_perm:[1,0,3,2] row_mask:0xf bank_mask:0xf
	v_add_f32_dpp v23, v23, v23 quad_perm:[1,0,3,2] row_mask:0xf bank_mask:0xf
	v_pk_mul_f32 v[84:85], v[2:3], v[64:65] op_sel:[0,0] op_sel_hi:[1,0]
	v_pk_mul_f32 v[86:87], v[4:5], v[64:65] op_sel:[0,1] op_sel_hi:[1,1]
	v_add_f32_dpp v58, v58, v58 row_ror:12 row_mask:0xf bank_mask:0x5
	v_add_f32_dpp v22, v22, v22 quad_perm:[2,3,0,1] row_mask:0xf bank_mask:0xf
	v_add_f32_dpp v23, v23, v23 quad_perm:[2,3,0,1] row_mask:0xf bank_mask:0xf
	v_pk_mul_f32 v[88:89], v[6:7], v[66:67] op_sel:[0,0] op_sel_hi:[1,0]
	v_pk_mul_f32 v[90:91], v[8:9], v[66:67] op_sel:[0,1] op_sel_hi:[1,1]
	v_add_f32_dpp v59, v59, v59 row_ror:4 row_mask:0xf bank_mask:0xa
	v_add_f32_dpp v22, v22, v22 row_half_mirror row_mask:0xf bank_mask:0xf
	v_add_f32_dpp v23, v23, v23 row_half_mirror row_mask:0xf bank_mask:0xf
	v_pk_fma_f32 v[84:85], v[72:73], v[80:81], v[84:85] op_sel:[0,0,0] op_sel_hi:[0,1,1]
	v_pk_fma_f32 v[86:87], v[72:73], v[80:81], v[86:87] op_sel:[1,0,0] op_sel_hi:[1,1,1]
	v_mov_b32_dpp v28, v29 quad_perm:[0,1,2,3] row_mask:0xf bank_mask:0xa
	v_add_f32_dpp v22, v22, v22 row_mirror row_mask:0xf bank_mask:0xf
	v_add_f32_dpp v23, v23, v23 row_mirror row_mask:0xf bank_mask:0xf
	v_pk_fma_f32 v[88:89], v[74:75], v[80:81], v[88:89] op_sel:[0,0,0] op_sel_hi:[0,1,1]
	v_pk_fma_f32 v[90:91], v[74:75], v[80:81], v[90:91] op_sel:[1,0,0] op_sel_hi:[1,1,1]
	v_mov_b32_dpp v58, v59 quad_perm:[0,1,2,3] row_mask:0xf bank_mask:0xa
	v_pk_fma_f32 v[2:3], v[68:69], v[22:23], v[84:85] op_sel:[0,0,0] op_sel_hi:[0,1,1] neg_lo:[1,0,0] neg_hi:[1,0,0]
	v_pk_fma_f32 v[4:5], v[68:69], v[22:23], v[86:87] op_sel:[1,0,0] op_sel_hi:[1,1,1] neg_lo:[1,0,0] neg_hi:[1,0,0]
	v_pk_fma_f32 v[6:7], v[70:71], v[22:23], v[88:89] op_sel:[0,0,0] op_sel_hi:[0,1,1] neg_lo:[1,0,0] neg_hi:[1,0,0]
	v_pk_fma_f32 v[8:9], v[70:71], v[22:23], v[90:91] op_sel:[1,0,0] op_sel_hi:[1,1,1] neg_lo:[1,0,0] neg_hi:[1,0,0]
	s_waitcnt lgkmcnt(0)
	ds_read_b128 v[60:63], v20 offset:5888
	ds_read_b128 v[64:67], v20 offset:14080
	ds_read_b64 v[80:81], v21 offset:46848
	ds_read_b128 v[72:75], v20 offset:30464
	ds_read_b128 v[68:71], v20 offset:22272
	ds_read_b128 v[92:95], v20 offset:38656
	v_pk_mul_f32 v[22:23], v[2:3], v[36:37] op_sel:[0,0] op_sel_hi:[1,0]
	v_pk_mul_f32 v[26:27], v[2:3], v[52:53] op_sel:[0,0] op_sel_hi:[1,0]
	v_pk_fma_f32 v[22:23], v[4:5], v[36:37], v[22:23] op_sel:[0,1,0] op_sel_hi:[1,1,1]
	v_pk_fma_f32 v[26:27], v[4:5], v[52:53], v[26:27] op_sel:[0,1,0] op_sel_hi:[1,1,1]
	v_pk_fma_f32 v[22:23], v[6:7], v[38:39], v[22:23] op_sel:[0,0,0] op_sel_hi:[1,0,1]
	v_pk_fma_f32 v[26:27], v[6:7], v[54:55], v[26:27] op_sel:[0,0,0] op_sel_hi:[1,0,1]
	v_pk_fma_f32 v[22:23], v[8:9], v[38:39], v[22:23] op_sel:[0,1,0] op_sel_hi:[1,1,1]
	v_pk_fma_f32 v[26:27], v[8:9], v[54:55], v[26:27] op_sel:[0,1,0] op_sel_hi:[1,1,1]
	v_add_f32_dpp v28, v28, v28 row_ror:8 row_mask:0xf bank_mask:0x3
	v_add_f32_dpp v58, v58, v58 row_ror:8 row_mask:0xf bank_mask:0xc
	v_add_f32_dpp v22, v22, v22 quad_perm:[1,0,3,2] row_mask:0xf bank_mask:0xf
	v_add_f32_dpp v23, v23, v23 quad_perm:[1,0,3,2] row_mask:0xf bank_mask:0xf
	v_pk_mul_f32 v[84:85], v[2:3], v[40:41] op_sel:[0,0] op_sel_hi:[1,0]
	v_pk_mul_f32 v[86:87], v[4:5], v[40:41] op_sel:[0,1] op_sel_hi:[1,1]
	v_mov_b32_dpp v28, v58 quad_perm:[0,1,2,3] row_mask:0xf bank_mask:0xc
	v_add_f32_dpp v22, v22, v22 quad_perm:[2,3,0,1] row_mask:0xf bank_mask:0xf
	v_add_f32_dpp v23, v23, v23 quad_perm:[2,3,0,1] row_mask:0xf bank_mask:0xf
	v_pk_mul_f32 v[88:89], v[6:7], v[42:43] op_sel:[0,0] op_sel_hi:[1,0]
	v_pk_mul_f32 v[90:91], v[8:9], v[42:43] op_sel:[0,1] op_sel_hi:[1,1]
	v_add_f32_dpp v28, v28, v28 quad_perm:[1,0,3,2] row_mask:0xf bank_mask:0xf
	v_add_f32_dpp v22, v22, v22 row_half_mirror row_mask:0xf bank_mask:0xf
	v_add_f32_dpp v23, v23, v23 row_half_mirror row_mask:0xf bank_mask:0xf
	v_pk_fma_f32 v[84:85], v[48:49], v[56:57], v[84:85] op_sel:[0,0,0] op_sel_hi:[0,1,1]
	v_pk_fma_f32 v[86:87], v[48:49], v[56:57], v[86:87] op_sel:[1,0,0] op_sel_hi:[1,1,1]
	v_add_f32_dpp v28, v28, v28 quad_perm:[2,3,0,1] row_mask:0xf bank_mask:0xf
	v_add_f32_dpp v22, v22, v22 row_mirror row_mask:0xf bank_mask:0xf
	v_add_f32_dpp v23, v23, v23 row_mirror row_mask:0xf bank_mask:0xf
	v_pk_fma_f32 v[88:89], v[50:51], v[56:57], v[88:89] op_sel:[0,0,0] op_sel_hi:[0,1,1]
	v_pk_fma_f32 v[90:91], v[50:51], v[56:57], v[90:91] op_sel:[1,0,0] op_sel_hi:[1,1,1]
	v_cndmask_b32_e64 v32, v32, v28, s[6:7]
	v_pk_fma_f32 v[2:3], v[44:45], v[22:23], v[84:85] op_sel:[0,0,0] op_sel_hi:[0,1,1] neg_lo:[1,0,0] neg_hi:[1,0,0]
	v_pk_fma_f32 v[4:5], v[44:45], v[22:23], v[86:87] op_sel:[1,0,0] op_sel_hi:[1,1,1] neg_lo:[1,0,0] neg_hi:[1,0,0]
	v_pk_fma_f32 v[6:7], v[46:47], v[22:23], v[88:89] op_sel:[0,0,0] op_sel_hi:[0,1,1] neg_lo:[1,0,0] neg_hi:[1,0,0]
	v_pk_fma_f32 v[8:9], v[46:47], v[22:23], v[90:91] op_sel:[1,0,0] op_sel_hi:[1,1,1] neg_lo:[1,0,0] neg_hi:[1,0,0]
	s_waitcnt lgkmcnt(0)
	ds_read_b128 v[36:39], v20 offset:6144
	ds_read_b128 v[40:43], v20 offset:14336
	ds_read_b64 v[56:57], v21 offset:47104
	ds_read_b128 v[48:51], v20 offset:30720
	ds_read_b128 v[44:47], v20 offset:22528
	ds_read_b128 v[52:55], v20 offset:38912
	v_pk_mul_f32 v[22:23], v[2:3], v[60:61] op_sel:[0,0] op_sel_hi:[1,0]
	v_pk_mul_f32 v[28:29], v[2:3], v[76:77] op_sel:[0,0] op_sel_hi:[1,0]
	v_pk_fma_f32 v[22:23], v[4:5], v[60:61], v[22:23] op_sel:[0,1,0] op_sel_hi:[1,1,1]
	v_pk_fma_f32 v[28:29], v[4:5], v[76:77], v[28:29] op_sel:[0,1,0] op_sel_hi:[1,1,1]
	v_pk_fma_f32 v[22:23], v[6:7], v[62:63], v[22:23] op_sel:[0,0,0] op_sel_hi:[1,0,1]
	v_pk_fma_f32 v[28:29], v[6:7], v[78:79], v[28:29] op_sel:[0,0,0] op_sel_hi:[1,0,1]
	v_pk_fma_f32 v[22:23], v[8:9], v[62:63], v[22:23] op_sel:[0,1,0] op_sel_hi:[1,1,1]
	v_pk_fma_f32 v[28:29], v[8:9], v[78:79], v[28:29] op_sel:[0,1,0] op_sel_hi:[1,1,1]
	v_add_f32_dpp v24, v24, v24 row_ror:12 row_mask:0xf bank_mask:0x5
	v_add_f32_dpp v25, v25, v25 row_ror:4 row_mask:0xf bank_mask:0xa
	v_add_f32_dpp v22, v22, v22 quad_perm:[1,0,3,2] row_mask:0xf bank_mask:0xf
	v_add_f32_dpp v23, v23, v23 quad_perm:[1,0,3,2] row_mask:0xf bank_mask:0xf
	v_pk_mul_f32 v[84:85], v[2:3], v[64:65] op_sel:[0,0] op_sel_hi:[1,0]
	v_pk_mul_f32 v[86:87], v[4:5], v[64:65] op_sel:[0,1] op_sel_hi:[1,1]
	v_add_f32_dpp v26, v26, v26 row_ror:12 row_mask:0xf bank_mask:0x5
	v_add_f32_dpp v22, v22, v22 quad_perm:[2,3,0,1] row_mask:0xf bank_mask:0xf
	v_add_f32_dpp v23, v23, v23 quad_perm:[2,3,0,1] row_mask:0xf bank_mask:0xf
	v_pk_mul_f32 v[88:89], v[6:7], v[66:67] op_sel:[0,0] op_sel_hi:[1,0]
	v_pk_mul_f32 v[90:91], v[8:9], v[66:67] op_sel:[0,1] op_sel_hi:[1,1]
	v_add_f32_dpp v27, v27, v27 row_ror:4 row_mask:0xf bank_mask:0xa
	v_add_f32_dpp v22, v22, v22 row_half_mirror row_mask:0xf bank_mask:0xf
	v_add_f32_dpp v23, v23, v23 row_half_mirror row_mask:0xf bank_mask:0xf
	v_pk_fma_f32 v[84:85], v[72:73], v[80:81], v[84:85] op_sel:[0,0,0] op_sel_hi:[0,1,1]
	v_pk_fma_f32 v[86:87], v[72:73], v[80:81], v[86:87] op_sel:[1,0,0] op_sel_hi:[1,1,1]
	v_mov_b32_dpp v24, v25 quad_perm:[0,1,2,3] row_mask:0xf bank_mask:0xa
	v_add_f32_dpp v22, v22, v22 row_mirror row_mask:0xf bank_mask:0xf
	v_add_f32_dpp v23, v23, v23 row_mirror row_mask:0xf bank_mask:0xf
	v_pk_fma_f32 v[88:89], v[74:75], v[80:81], v[88:89] op_sel:[0,0,0] op_sel_hi:[0,1,1]
	v_pk_fma_f32 v[90:91], v[74:75], v[80:81], v[90:91] op_sel:[1,0,0] op_sel_hi:[1,1,1]
	v_mov_b32_dpp v26, v27 quad_perm:[0,1,2,3] row_mask:0xf bank_mask:0xa
	v_pk_fma_f32 v[2:3], v[68:69], v[22:23], v[84:85] op_sel:[0,0,0] op_sel_hi:[0,1,1] neg_lo:[1,0,0] neg_hi:[1,0,0]
	v_pk_fma_f32 v[4:5], v[68:69], v[22:23], v[86:87] op_sel:[1,0,0] op_sel_hi:[1,1,1] neg_lo:[1,0,0] neg_hi:[1,0,0]
	v_pk_fma_f32 v[6:7], v[70:71], v[22:23], v[88:89] op_sel:[0,0,0] op_sel_hi:[0,1,1] neg_lo:[1,0,0] neg_hi:[1,0,0]
	v_pk_fma_f32 v[8:9], v[70:71], v[22:23], v[90:91] op_sel:[1,0,0] op_sel_hi:[1,1,1] neg_lo:[1,0,0] neg_hi:[1,0,0]
	s_waitcnt lgkmcnt(0)
	ds_read_b128 v[60:63], v20 offset:6400
	ds_read_b128 v[64:67], v20 offset:14592
	ds_read_b64 v[80:81], v21 offset:47360
	ds_read_b128 v[72:75], v20 offset:30976
	ds_read_b128 v[68:71], v20 offset:22784
	ds_read_b128 v[76:79], v20 offset:39168
	v_pk_mul_f32 v[22:23], v[2:3], v[36:37] op_sel:[0,0] op_sel_hi:[1,0]
	v_pk_mul_f32 v[58:59], v[2:3], v[92:93] op_sel:[0,0] op_sel_hi:[1,0]
	v_pk_fma_f32 v[22:23], v[4:5], v[36:37], v[22:23] op_sel:[0,1,0] op_sel_hi:[1,1,1]
	v_pk_fma_f32 v[58:59], v[4:5], v[92:93], v[58:59] op_sel:[0,1,0] op_sel_hi:[1,1,1]
	v_pk_fma_f32 v[22:23], v[6:7], v[38:39], v[22:23] op_sel:[0,0,0] op_sel_hi:[1,0,1]
	v_pk_fma_f32 v[58:59], v[6:7], v[94:95], v[58:59] op_sel:[0,0,0] op_sel_hi:[1,0,1]
	v_pk_fma_f32 v[22:23], v[8:9], v[38:39], v[22:23] op_sel:[0,1,0] op_sel_hi:[1,1,1]
	v_pk_fma_f32 v[58:59], v[8:9], v[94:95], v[58:59] op_sel:[0,1,0] op_sel_hi:[1,1,1]
	v_add_f32_dpp v24, v24, v24 row_ror:8 row_mask:0xf bank_mask:0x3
	v_add_f32_dpp v26, v26, v26 row_ror:8 row_mask:0xf bank_mask:0xc
	v_add_f32_dpp v22, v22, v22 quad_perm:[1,0,3,2] row_mask:0xf bank_mask:0xf
	v_add_f32_dpp v23, v23, v23 quad_perm:[1,0,3,2] row_mask:0xf bank_mask:0xf
	v_pk_mul_f32 v[84:85], v[2:3], v[40:41] op_sel:[0,0] op_sel_hi:[1,0]
	v_pk_mul_f32 v[86:87], v[4:5], v[40:41] op_sel:[0,1] op_sel_hi:[1,1]
	v_mov_b32_dpp v24, v26 quad_perm:[0,1,2,3] row_mask:0xf bank_mask:0xc
	v_add_f32_dpp v22, v22, v22 quad_perm:[2,3,0,1] row_mask:0xf bank_mask:0xf
	v_add_f32_dpp v23, v23, v23 quad_perm:[2,3,0,1] row_mask:0xf bank_mask:0xf
	v_pk_mul_f32 v[88:89], v[6:7], v[42:43] op_sel:[0,0] op_sel_hi:[1,0]
	v_pk_mul_f32 v[90:91], v[8:9], v[42:43] op_sel:[0,1] op_sel_hi:[1,1]
	v_add_f32_dpp v24, v24, v24 quad_perm:[1,0,3,2] row_mask:0xf bank_mask:0xf
	v_add_f32_dpp v22, v22, v22 row_half_mirror row_mask:0xf bank_mask:0xf
	v_add_f32_dpp v23, v23, v23 row_half_mirror row_mask:0xf bank_mask:0xf
	v_pk_fma_f32 v[84:85], v[48:49], v[56:57], v[84:85] op_sel:[0,0,0] op_sel_hi:[0,1,1]
	v_pk_fma_f32 v[86:87], v[48:49], v[56:57], v[86:87] op_sel:[1,0,0] op_sel_hi:[1,1,1]
	v_add_f32_dpp v24, v24, v24 quad_perm:[2,3,0,1] row_mask:0xf bank_mask:0xf
	v_add_f32_dpp v22, v22, v22 row_mirror row_mask:0xf bank_mask:0xf
	v_add_f32_dpp v23, v23, v23 row_mirror row_mask:0xf bank_mask:0xf
	v_pk_fma_f32 v[88:89], v[50:51], v[56:57], v[88:89] op_sel:[0,0,0] op_sel_hi:[0,1,1]
	v_pk_fma_f32 v[90:91], v[50:51], v[56:57], v[90:91] op_sel:[1,0,0] op_sel_hi:[1,1,1]
	v_cndmask_b32_e64 v32, v32, v24, s[8:9]
	v_pk_fma_f32 v[2:3], v[44:45], v[22:23], v[84:85] op_sel:[0,0,0] op_sel_hi:[0,1,1] neg_lo:[1,0,0] neg_hi:[1,0,0]
	v_pk_fma_f32 v[4:5], v[44:45], v[22:23], v[86:87] op_sel:[1,0,0] op_sel_hi:[1,1,1] neg_lo:[1,0,0] neg_hi:[1,0,0]
	v_pk_fma_f32 v[6:7], v[46:47], v[22:23], v[88:89] op_sel:[0,0,0] op_sel_hi:[0,1,1] neg_lo:[1,0,0] neg_hi:[1,0,0]
	v_pk_fma_f32 v[8:9], v[46:47], v[22:23], v[90:91] op_sel:[1,0,0] op_sel_hi:[1,1,1] neg_lo:[1,0,0] neg_hi:[1,0,0]
	s_waitcnt lgkmcnt(0)
	ds_read_b128 v[36:39], v20 offset:6656
	ds_read_b128 v[40:43], v20 offset:14848
	ds_read_b64 v[56:57], v21 offset:47616
	ds_read_b128 v[48:51], v20 offset:31232
	ds_read_b128 v[44:47], v20 offset:23040
	ds_read_b128 v[92:95], v20 offset:39424
	v_pk_mul_f32 v[22:23], v[2:3], v[60:61] op_sel:[0,0] op_sel_hi:[1,0]
	v_pk_mul_f32 v[24:25], v[2:3], v[52:53] op_sel:[0,0] op_sel_hi:[1,0]
	v_pk_fma_f32 v[22:23], v[4:5], v[60:61], v[22:23] op_sel:[0,1,0] op_sel_hi:[1,1,1]
	v_pk_fma_f32 v[24:25], v[4:5], v[52:53], v[24:25] op_sel:[0,1,0] op_sel_hi:[1,1,1]
	v_pk_fma_f32 v[22:23], v[6:7], v[62:63], v[22:23] op_sel:[0,0,0] op_sel_hi:[1,0,1]
	v_pk_fma_f32 v[24:25], v[6:7], v[54:55], v[24:25] op_sel:[0,0,0] op_sel_hi:[1,0,1]
	v_pk_fma_f32 v[22:23], v[8:9], v[62:63], v[22:23] op_sel:[0,1,0] op_sel_hi:[1,1,1]
	v_pk_fma_f32 v[24:25], v[8:9], v[54:55], v[24:25] op_sel:[0,1,0] op_sel_hi:[1,1,1]
	v_add_f32_dpp v28, v28, v28 row_ror:12 row_mask:0xf bank_mask:0x5
	v_add_f32_dpp v29, v29, v29 row_ror:4 row_mask:0xf bank_mask:0xa
	v_add_f32_dpp v22, v22, v22 quad_perm:[1,0,3,2] row_mask:0xf bank_mask:0xf
	v_add_f32_dpp v23, v23, v23 quad_perm:[1,0,3,2] row_mask:0xf bank_mask:0xf
	v_pk_mul_f32 v[84:85], v[2:3], v[64:65] op_sel:[0,0] op_sel_hi:[1,0]
	v_pk_mul_f32 v[86:87], v[4:5], v[64:65] op_sel:[0,1] op_sel_hi:[1,1]
	v_add_f32_dpp v58, v58, v58 row_ror:12 row_mask:0xf bank_mask:0x5
	v_add_f32_dpp v22, v22, v22 quad_perm:[2,3,0,1] row_mask:0xf bank_mask:0xf
	v_add_f32_dpp v23, v23, v23 quad_perm:[2,3,0,1] row_mask:0xf bank_mask:0xf
	v_pk_mul_f32 v[88:89], v[6:7], v[66:67] op_sel:[0,0] op_sel_hi:[1,0]
	v_pk_mul_f32 v[90:91], v[8:9], v[66:67] op_sel:[0,1] op_sel_hi:[1,1]
	v_add_f32_dpp v59, v59, v59 row_ror:4 row_mask:0xf bank_mask:0xa
	v_add_f32_dpp v22, v22, v22 row_half_mirror row_mask:0xf bank_mask:0xf
	v_add_f32_dpp v23, v23, v23 row_half_mirror row_mask:0xf bank_mask:0xf
	v_pk_fma_f32 v[84:85], v[72:73], v[80:81], v[84:85] op_sel:[0,0,0] op_sel_hi:[0,1,1]
	v_pk_fma_f32 v[86:87], v[72:73], v[80:81], v[86:87] op_sel:[1,0,0] op_sel_hi:[1,1,1]
	v_mov_b32_dpp v28, v29 quad_perm:[0,1,2,3] row_mask:0xf bank_mask:0xa
	v_add_f32_dpp v22, v22, v22 row_mirror row_mask:0xf bank_mask:0xf
	v_add_f32_dpp v23, v23, v23 row_mirror row_mask:0xf bank_mask:0xf
	v_pk_fma_f32 v[88:89], v[74:75], v[80:81], v[88:89] op_sel:[0,0,0] op_sel_hi:[0,1,1]
	v_pk_fma_f32 v[90:91], v[74:75], v[80:81], v[90:91] op_sel:[1,0,0] op_sel_hi:[1,1,1]
	v_mov_b32_dpp v58, v59 quad_perm:[0,1,2,3] row_mask:0xf bank_mask:0xa
	v_pk_fma_f32 v[2:3], v[68:69], v[22:23], v[84:85] op_sel:[0,0,0] op_sel_hi:[0,1,1] neg_lo:[1,0,0] neg_hi:[1,0,0]
	v_pk_fma_f32 v[4:5], v[68:69], v[22:23], v[86:87] op_sel:[1,0,0] op_sel_hi:[1,1,1] neg_lo:[1,0,0] neg_hi:[1,0,0]
	v_pk_fma_f32 v[6:7], v[70:71], v[22:23], v[88:89] op_sel:[0,0,0] op_sel_hi:[0,1,1] neg_lo:[1,0,0] neg_hi:[1,0,0]
	v_pk_fma_f32 v[8:9], v[70:71], v[22:23], v[90:91] op_sel:[1,0,0] op_sel_hi:[1,1,1] neg_lo:[1,0,0] neg_hi:[1,0,0]
	s_waitcnt lgkmcnt(0)
	ds_read_b128 v[60:63], v20 offset:6912
	ds_read_b128 v[64:67], v20 offset:15104
	ds_read_b64 v[80:81], v21 offset:47872
	ds_read_b128 v[72:75], v20 offset:31488
	ds_read_b128 v[68:71], v20 offset:23296
	ds_read_b128 v[52:55], v20 offset:39680
	v_pk_mul_f32 v[22:23], v[2:3], v[36:37] op_sel:[0,0] op_sel_hi:[1,0]
	v_pk_mul_f32 v[26:27], v[2:3], v[76:77] op_sel:[0,0] op_sel_hi:[1,0]
	v_pk_fma_f32 v[22:23], v[4:5], v[36:37], v[22:23] op_sel:[0,1,0] op_sel_hi:[1,1,1]
	v_pk_fma_f32 v[26:27], v[4:5], v[76:77], v[26:27] op_sel:[0,1,0] op_sel_hi:[1,1,1]
	v_pk_fma_f32 v[22:23], v[6:7], v[38:39], v[22:23] op_sel:[0,0,0] op_sel_hi:[1,0,1]
	v_pk_fma_f32 v[26:27], v[6:7], v[78:79], v[26:27] op_sel:[0,0,0] op_sel_hi:[1,0,1]
	v_pk_fma_f32 v[22:23], v[8:9], v[38:39], v[22:23] op_sel:[0,1,0] op_sel_hi:[1,1,1]
	v_pk_fma_f32 v[26:27], v[8:9], v[78:79], v[26:27] op_sel:[0,1,0] op_sel_hi:[1,1,1]
	v_add_f32_dpp v28, v28, v28 row_ror:8 row_mask:0xf bank_mask:0x3
	v_add_f32_dpp v58, v58, v58 row_ror:8 row_mask:0xf bank_mask:0xc
	v_add_f32_dpp v22, v22, v22 quad_perm:[1,0,3,2] row_mask:0xf bank_mask:0xf
	v_add_f32_dpp v23, v23, v23 quad_perm:[1,0,3,2] row_mask:0xf bank_mask:0xf
	v_pk_mul_f32 v[84:85], v[2:3], v[40:41] op_sel:[0,0] op_sel_hi:[1,0]
	v_pk_mul_f32 v[86:87], v[4:5], v[40:41] op_sel:[0,1] op_sel_hi:[1,1]
	v_mov_b32_dpp v28, v58 quad_perm:[0,1,2,3] row_mask:0xf bank_mask:0xc
	v_add_f32_dpp v22, v22, v22 quad_perm:[2,3,0,1] row_mask:0xf bank_mask:0xf
	v_add_f32_dpp v23, v23, v23 quad_perm:[2,3,0,1] row_mask:0xf bank_mask:0xf
	v_pk_mul_f32 v[88:89], v[6:7], v[42:43] op_sel:[0,0] op_sel_hi:[1,0]
	v_pk_mul_f32 v[90:91], v[8:9], v[42:43] op_sel:[0,1] op_sel_hi:[1,1]
	v_add_f32_dpp v28, v28, v28 quad_perm:[1,0,3,2] row_mask:0xf bank_mask:0xf
	v_add_f32_dpp v22, v22, v22 row_half_mirror row_mask:0xf bank_mask:0xf
	v_add_f32_dpp v23, v23, v23 row_half_mirror row_mask:0xf bank_mask:0xf
	v_pk_fma_f32 v[84:85], v[48:49], v[56:57], v[84:85] op_sel:[0,0,0] op_sel_hi:[0,1,1]
	v_pk_fma_f32 v[86:87], v[48:49], v[56:57], v[86:87] op_sel:[1,0,0] op_sel_hi:[1,1,1]
	v_add_f32_dpp v28, v28, v28 quad_perm:[2,3,0,1] row_mask:0xf bank_mask:0xf
	v_add_f32_dpp v22, v22, v22 row_mirror row_mask:0xf bank_mask:0xf
	v_add_f32_dpp v23, v23, v23 row_mirror row_mask:0xf bank_mask:0xf
	v_pk_fma_f32 v[88:89], v[50:51], v[56:57], v[88:89] op_sel:[0,0,0] op_sel_hi:[0,1,1]
	v_pk_fma_f32 v[90:91], v[50:51], v[56:57], v[90:91] op_sel:[1,0,0] op_sel_hi:[1,1,1]
	v_cndmask_b32_e64 v32, v32, v28, s[10:11]
	v_pk_fma_f32 v[2:3], v[44:45], v[22:23], v[84:85] op_sel:[0,0,0] op_sel_hi:[0,1,1] neg_lo:[1,0,0] neg_hi:[1,0,0]
	v_pk_fma_f32 v[4:5], v[44:45], v[22:23], v[86:87] op_sel:[1,0,0] op_sel_hi:[1,1,1] neg_lo:[1,0,0] neg_hi:[1,0,0]
	v_pk_fma_f32 v[6:7], v[46:47], v[22:23], v[88:89] op_sel:[0,0,0] op_sel_hi:[0,1,1] neg_lo:[1,0,0] neg_hi:[1,0,0]
	v_pk_fma_f32 v[8:9], v[46:47], v[22:23], v[90:91] op_sel:[1,0,0] op_sel_hi:[1,1,1] neg_lo:[1,0,0] neg_hi:[1,0,0]
	s_waitcnt lgkmcnt(0)
	ds_read_b128 v[36:39], v20 offset:7168
	ds_read_b128 v[40:43], v20 offset:15360
	ds_read_b64 v[56:57], v21 offset:48128
	ds_read_b128 v[48:51], v20 offset:31744
	ds_read_b128 v[44:47], v20 offset:23552
	ds_read_b128 v[76:79], v20 offset:39936
	v_pk_mul_f32 v[22:23], v[2:3], v[60:61] op_sel:[0,0] op_sel_hi:[1,0]
	v_pk_mul_f32 v[28:29], v[2:3], v[92:93] op_sel:[0,0] op_sel_hi:[1,0]
	v_pk_fma_f32 v[22:23], v[4:5], v[60:61], v[22:23] op_sel:[0,1,0] op_sel_hi:[1,1,1]
	v_pk_fma_f32 v[28:29], v[4:5], v[92:93], v[28:29] op_sel:[0,1,0] op_sel_hi:[1,1,1]
	v_pk_fma_f32 v[22:23], v[6:7], v[62:63], v[22:23] op_sel:[0,0,0] op_sel_hi:[1,0,1]
	v_pk_fma_f32 v[28:29], v[6:7], v[94:95], v[28:29] op_sel:[0,0,0] op_sel_hi:[1,0,1]
	v_pk_fma_f32 v[22:23], v[8:9], v[62:63], v[22:23] op_sel:[0,1,0] op_sel_hi:[1,1,1]
	v_pk_fma_f32 v[28:29], v[8:9], v[94:95], v[28:29] op_sel:[0,1,0] op_sel_hi:[1,1,1]
	v_add_f32_dpp v24, v24, v24 row_ror:12 row_mask:0xf bank_mask:0x5
	v_add_f32_dpp v25, v25, v25 row_ror:4 row_mask:0xf bank_mask:0xa
	v_add_f32_dpp v22, v22, v22 quad_perm:[1,0,3,2] row_mask:0xf bank_mask:0xf
	v_add_f32_dpp v23, v23, v23 quad_perm:[1,0,3,2] row_mask:0xf bank_mask:0xf
	v_pk_mul_f32 v[84:85], v[2:3], v[64:65] op_sel:[0,0] op_sel_hi:[1,0]
	v_pk_mul_f32 v[86:87], v[4:5], v[64:65] op_sel:[0,1] op_sel_hi:[1,1]
	v_add_f32_dpp v26, v26, v26 row_ror:12 row_mask:0xf bank_mask:0x5
	v_add_f32_dpp v22, v22, v22 quad_perm:[2,3,0,1] row_mask:0xf bank_mask:0xf
	v_add_f32_dpp v23, v23, v23 quad_perm:[2,3,0,1] row_mask:0xf bank_mask:0xf
	v_pk_mul_f32 v[88:89], v[6:7], v[66:67] op_sel:[0,0] op_sel_hi:[1,0]
	v_pk_mul_f32 v[90:91], v[8:9], v[66:67] op_sel:[0,1] op_sel_hi:[1,1]
	v_add_f32_dpp v27, v27, v27 row_ror:4 row_mask:0xf bank_mask:0xa
	v_add_f32_dpp v22, v22, v22 row_half_mirror row_mask:0xf bank_mask:0xf
	v_add_f32_dpp v23, v23, v23 row_half_mirror row_mask:0xf bank_mask:0xf
	v_pk_fma_f32 v[84:85], v[72:73], v[80:81], v[84:85] op_sel:[0,0,0] op_sel_hi:[0,1,1]
	v_pk_fma_f32 v[86:87], v[72:73], v[80:81], v[86:87] op_sel:[1,0,0] op_sel_hi:[1,1,1]
	v_mov_b32_dpp v24, v25 quad_perm:[0,1,2,3] row_mask:0xf bank_mask:0xa
	v_add_f32_dpp v22, v22, v22 row_mirror row_mask:0xf bank_mask:0xf
	v_add_f32_dpp v23, v23, v23 row_mirror row_mask:0xf bank_mask:0xf
	v_pk_fma_f32 v[88:89], v[74:75], v[80:81], v[88:89] op_sel:[0,0,0] op_sel_hi:[0,1,1]
	v_pk_fma_f32 v[90:91], v[74:75], v[80:81], v[90:91] op_sel:[1,0,0] op_sel_hi:[1,1,1]
	v_mov_b32_dpp v26, v27 quad_perm:[0,1,2,3] row_mask:0xf bank_mask:0xa
	v_pk_fma_f32 v[2:3], v[68:69], v[22:23], v[84:85] op_sel:[0,0,0] op_sel_hi:[0,1,1] neg_lo:[1,0,0] neg_hi:[1,0,0]
	v_pk_fma_f32 v[4:5], v[68:69], v[22:23], v[86:87] op_sel:[1,0,0] op_sel_hi:[1,1,1] neg_lo:[1,0,0] neg_hi:[1,0,0]
	v_pk_fma_f32 v[6:7], v[70:71], v[22:23], v[88:89] op_sel:[0,0,0] op_sel_hi:[0,1,1] neg_lo:[1,0,0] neg_hi:[1,0,0]
	v_pk_fma_f32 v[8:9], v[70:71], v[22:23], v[90:91] op_sel:[1,0,0] op_sel_hi:[1,1,1] neg_lo:[1,0,0] neg_hi:[1,0,0]
	s_waitcnt lgkmcnt(0)
	ds_read_b128 v[60:63], v20 offset:7424
	ds_read_b128 v[64:67], v20 offset:15616
	ds_read_b64 v[80:81], v21 offset:48384
	ds_read_b128 v[72:75], v20 offset:32000
	ds_read_b128 v[68:71], v20 offset:23808
	ds_read_b128 v[92:95], v20 offset:40192
	v_pk_mul_f32 v[22:23], v[2:3], v[36:37] op_sel:[0,0] op_sel_hi:[1,0]
	v_pk_mul_f32 v[58:59], v[2:3], v[52:53] op_sel:[0,0] op_sel_hi:[1,0]
	v_pk_fma_f32 v[22:23], v[4:5], v[36:37], v[22:23] op_sel:[0,1,0] op_sel_hi:[1,1,1]
	v_pk_fma_f32 v[58:59], v[4:5], v[52:53], v[58:59] op_sel:[0,1,0] op_sel_hi:[1,1,1]
	v_pk_fma_f32 v[22:23], v[6:7], v[38:39], v[22:23] op_sel:[0,0,0] op_sel_hi:[1,0,1]
	v_pk_fma_f32 v[58:59], v[6:7], v[54:55], v[58:59] op_sel:[0,0,0] op_sel_hi:[1,0,1]
	v_pk_fma_f32 v[22:23], v[8:9], v[38:39], v[22:23] op_sel:[0,1,0] op_sel_hi:[1,1,1]
	v_pk_fma_f32 v[58:59], v[8:9], v[54:55], v[58:59] op_sel:[0,1,0] op_sel_hi:[1,1,1]
	v_add_f32_dpp v24, v24, v24 row_ror:8 row_mask:0xf bank_mask:0x3
	v_add_f32_dpp v26, v26, v26 row_ror:8 row_mask:0xf bank_mask:0xc
	v_add_f32_dpp v22, v22, v22 quad_perm:[1,0,3,2] row_mask:0xf bank_mask:0xf
	v_add_f32_dpp v23, v23, v23 quad_perm:[1,0,3,2] row_mask:0xf bank_mask:0xf
	v_pk_mul_f32 v[84:85], v[2:3], v[40:41] op_sel:[0,0] op_sel_hi:[1,0]
	v_pk_mul_f32 v[86:87], v[4:5], v[40:41] op_sel:[0,1] op_sel_hi:[1,1]
	v_mov_b32_dpp v24, v26 quad_perm:[0,1,2,3] row_mask:0xf bank_mask:0xc
	v_add_f32_dpp v22, v22, v22 quad_perm:[2,3,0,1] row_mask:0xf bank_mask:0xf
	v_add_f32_dpp v23, v23, v23 quad_perm:[2,3,0,1] row_mask:0xf bank_mask:0xf
	v_pk_mul_f32 v[88:89], v[6:7], v[42:43] op_sel:[0,0] op_sel_hi:[1,0]
	v_pk_mul_f32 v[90:91], v[8:9], v[42:43] op_sel:[0,1] op_sel_hi:[1,1]
	v_add_f32_dpp v24, v24, v24 quad_perm:[1,0,3,2] row_mask:0xf bank_mask:0xf
	v_add_f32_dpp v22, v22, v22 row_half_mirror row_mask:0xf bank_mask:0xf
	v_add_f32_dpp v23, v23, v23 row_half_mirror row_mask:0xf bank_mask:0xf
	v_pk_fma_f32 v[84:85], v[48:49], v[56:57], v[84:85] op_sel:[0,0,0] op_sel_hi:[0,1,1]
	v_pk_fma_f32 v[86:87], v[48:49], v[56:57], v[86:87] op_sel:[1,0,0] op_sel_hi:[1,1,1]
	v_add_f32_dpp v24, v24, v24 quad_perm:[2,3,0,1] row_mask:0xf bank_mask:0xf
	v_add_f32_dpp v22, v22, v22 row_mirror row_mask:0xf bank_mask:0xf
	v_add_f32_dpp v23, v23, v23 row_mirror row_mask:0xf bank_mask:0xf
	v_pk_fma_f32 v[88:89], v[50:51], v[56:57], v[88:89] op_sel:[0,0,0] op_sel_hi:[0,1,1]
	v_pk_fma_f32 v[90:91], v[50:51], v[56:57], v[90:91] op_sel:[1,0,0] op_sel_hi:[1,1,1]
	v_cndmask_b32_e64 v33, 0, v24, s[0:1]
	v_pk_fma_f32 v[2:3], v[44:45], v[22:23], v[84:85] op_sel:[0,0,0] op_sel_hi:[0,1,1] neg_lo:[1,0,0] neg_hi:[1,0,0]
	v_pk_fma_f32 v[4:5], v[44:45], v[22:23], v[86:87] op_sel:[1,0,0] op_sel_hi:[1,1,1] neg_lo:[1,0,0] neg_hi:[1,0,0]
	v_pk_fma_f32 v[6:7], v[46:47], v[22:23], v[88:89] op_sel:[0,0,0] op_sel_hi:[0,1,1] neg_lo:[1,0,0] neg_hi:[1,0,0]
	v_pk_fma_f32 v[8:9], v[46:47], v[22:23], v[90:91] op_sel:[1,0,0] op_sel_hi:[1,1,1] neg_lo:[1,0,0] neg_hi:[1,0,0]
	s_waitcnt lgkmcnt(0)
	ds_read_b128 v[36:39], v20 offset:7680
	ds_read_b128 v[40:43], v20 offset:15872
	ds_read_b64 v[56:57], v21 offset:48640
	ds_read_b128 v[48:51], v20 offset:32256
	ds_read_b128 v[44:47], v20 offset:24064
	ds_read_b128 v[52:55], v20 offset:40448
	v_pk_mul_f32 v[22:23], v[2:3], v[60:61] op_sel:[0,0] op_sel_hi:[1,0]
	v_pk_mul_f32 v[24:25], v[2:3], v[76:77] op_sel:[0,0] op_sel_hi:[1,0]
	v_pk_fma_f32 v[22:23], v[4:5], v[60:61], v[22:23] op_sel:[0,1,0] op_sel_hi:[1,1,1]
	v_pk_fma_f32 v[24:25], v[4:5], v[76:77], v[24:25] op_sel:[0,1,0] op_sel_hi:[1,1,1]
	v_pk_fma_f32 v[22:23], v[6:7], v[62:63], v[22:23] op_sel:[0,0,0] op_sel_hi:[1,0,1]
	v_pk_fma_f32 v[24:25], v[6:7], v[78:79], v[24:25] op_sel:[0,0,0] op_sel_hi:[1,0,1]
	v_pk_fma_f32 v[22:23], v[8:9], v[62:63], v[22:23] op_sel:[0,1,0] op_sel_hi:[1,1,1]
	v_pk_fma_f32 v[24:25], v[8:9], v[78:79], v[24:25] op_sel:[0,1,0] op_sel_hi:[1,1,1]
	v_add_f32_dpp v28, v28, v28 row_ror:12 row_mask:0xf bank_mask:0x5
	v_add_f32_dpp v29, v29, v29 row_ror:4 row_mask:0xf bank_mask:0xa
	v_add_f32_dpp v22, v22, v22 quad_perm:[1,0,3,2] row_mask:0xf bank_mask:0xf
	v_add_f32_dpp v23, v23, v23 quad_perm:[1,0,3,2] row_mask:0xf bank_mask:0xf
	v_pk_mul_f32 v[84:85], v[2:3], v[64:65] op_sel:[0,0] op_sel_hi:[1,0]
	v_pk_mul_f32 v[86:87], v[4:5], v[64:65] op_sel:[0,1] op_sel_hi:[1,1]
	v_add_f32_dpp v58, v58, v58 row_ror:12 row_mask:0xf bank_mask:0x5
	v_add_f32_dpp v22, v22, v22 quad_perm:[2,3,0,1] row_mask:0xf bank_mask:0xf
	v_add_f32_dpp v23, v23, v23 quad_perm:[2,3,0,1] row_mask:0xf bank_mask:0xf
	v_pk_mul_f32 v[88:89], v[6:7], v[66:67] op_sel:[0,0] op_sel_hi:[1,0]
	v_pk_mul_f32 v[90:91], v[8:9], v[66:67] op_sel:[0,1] op_sel_hi:[1,1]
	v_add_f32_dpp v59, v59, v59 row_ror:4 row_mask:0xf bank_mask:0xa
	v_add_f32_dpp v22, v22, v22 row_half_mirror row_mask:0xf bank_mask:0xf
	v_add_f32_dpp v23, v23, v23 row_half_mirror row_mask:0xf bank_mask:0xf
	v_pk_fma_f32 v[84:85], v[72:73], v[80:81], v[84:85] op_sel:[0,0,0] op_sel_hi:[0,1,1]
	v_pk_fma_f32 v[86:87], v[72:73], v[80:81], v[86:87] op_sel:[1,0,0] op_sel_hi:[1,1,1]
	v_mov_b32_dpp v28, v29 quad_perm:[0,1,2,3] row_mask:0xf bank_mask:0xa
	v_add_f32_dpp v22, v22, v22 row_mirror row_mask:0xf bank_mask:0xf
	v_add_f32_dpp v23, v23, v23 row_mirror row_mask:0xf bank_mask:0xf
	v_pk_fma_f32 v[88:89], v[74:75], v[80:81], v[88:89] op_sel:[0,0,0] op_sel_hi:[0,1,1]
	v_pk_fma_f32 v[90:91], v[74:75], v[80:81], v[90:91] op_sel:[1,0,0] op_sel_hi:[1,1,1]
	v_mov_b32_dpp v58, v59 quad_perm:[0,1,2,3] row_mask:0xf bank_mask:0xa
	v_pk_fma_f32 v[2:3], v[68:69], v[22:23], v[84:85] op_sel:[0,0,0] op_sel_hi:[0,1,1] neg_lo:[1,0,0] neg_hi:[1,0,0]
	v_pk_fma_f32 v[4:5], v[68:69], v[22:23], v[86:87] op_sel:[1,0,0] op_sel_hi:[1,1,1] neg_lo:[1,0,0] neg_hi:[1,0,0]
	v_pk_fma_f32 v[6:7], v[70:71], v[22:23], v[88:89] op_sel:[0,0,0] op_sel_hi:[0,1,1] neg_lo:[1,0,0] neg_hi:[1,0,0]
	v_pk_fma_f32 v[8:9], v[70:71], v[22:23], v[90:91] op_sel:[1,0,0] op_sel_hi:[1,1,1] neg_lo:[1,0,0] neg_hi:[1,0,0]
	s_waitcnt lgkmcnt(0)
	ds_read_b128 v[60:63], v20 offset:7936
	ds_read_b128 v[64:67], v20 offset:16128
	ds_read_b64 v[80:81], v21 offset:48896
	ds_read_b128 v[72:75], v20 offset:32512
	ds_read_b128 v[68:71], v20 offset:24320
	ds_read_b128 v[76:79], v20 offset:40704
	v_pk_mul_f32 v[22:23], v[2:3], v[36:37] op_sel:[0,0] op_sel_hi:[1,0]
	v_pk_mul_f32 v[26:27], v[2:3], v[92:93] op_sel:[0,0] op_sel_hi:[1,0]
	v_pk_fma_f32 v[22:23], v[4:5], v[36:37], v[22:23] op_sel:[0,1,0] op_sel_hi:[1,1,1]
	v_pk_fma_f32 v[26:27], v[4:5], v[92:93], v[26:27] op_sel:[0,1,0] op_sel_hi:[1,1,1]
	v_pk_fma_f32 v[22:23], v[6:7], v[38:39], v[22:23] op_sel:[0,0,0] op_sel_hi:[1,0,1]
	v_pk_fma_f32 v[26:27], v[6:7], v[94:95], v[26:27] op_sel:[0,0,0] op_sel_hi:[1,0,1]
	v_pk_fma_f32 v[22:23], v[8:9], v[38:39], v[22:23] op_sel:[0,1,0] op_sel_hi:[1,1,1]
	v_pk_fma_f32 v[26:27], v[8:9], v[94:95], v[26:27] op_sel:[0,1,0] op_sel_hi:[1,1,1]
	v_add_f32_dpp v28, v28, v28 row_ror:8 row_mask:0xf bank_mask:0x3
	v_add_f32_dpp v58, v58, v58 row_ror:8 row_mask:0xf bank_mask:0xc
	v_add_f32_dpp v22, v22, v22 quad_perm:[1,0,3,2] row_mask:0xf bank_mask:0xf
	v_add_f32_dpp v23, v23, v23 quad_perm:[1,0,3,2] row_mask:0xf bank_mask:0xf
	v_pk_mul_f32 v[84:85], v[2:3], v[40:41] op_sel:[0,0] op_sel_hi:[1,0]
	v_pk_mul_f32 v[86:87], v[4:5], v[40:41] op_sel:[0,1] op_sel_hi:[1,1]
	v_mov_b32_dpp v28, v58 quad_perm:[0,1,2,3] row_mask:0xf bank_mask:0xc
	v_add_f32_dpp v22, v22, v22 quad_perm:[2,3,0,1] row_mask:0xf bank_mask:0xf
	v_add_f32_dpp v23, v23, v23 quad_perm:[2,3,0,1] row_mask:0xf bank_mask:0xf
	v_pk_mul_f32 v[88:89], v[6:7], v[42:43] op_sel:[0,0] op_sel_hi:[1,0]
	v_pk_mul_f32 v[90:91], v[8:9], v[42:43] op_sel:[0,1] op_sel_hi:[1,1]
	v_add_f32_dpp v28, v28, v28 quad_perm:[1,0,3,2] row_mask:0xf bank_mask:0xf
	v_add_f32_dpp v22, v22, v22 row_half_mirror row_mask:0xf bank_mask:0xf
	v_add_f32_dpp v23, v23, v23 row_half_mirror row_mask:0xf bank_mask:0xf
	v_pk_fma_f32 v[84:85], v[48:49], v[56:57], v[84:85] op_sel:[0,0,0] op_sel_hi:[0,1,1]
	v_pk_fma_f32 v[86:87], v[48:49], v[56:57], v[86:87] op_sel:[1,0,0] op_sel_hi:[1,1,1]
	v_add_f32_dpp v28, v28, v28 quad_perm:[2,3,0,1] row_mask:0xf bank_mask:0xf
	v_add_f32_dpp v22, v22, v22 row_mirror row_mask:0xf bank_mask:0xf
	v_add_f32_dpp v23, v23, v23 row_mirror row_mask:0xf bank_mask:0xf
	v_pk_fma_f32 v[88:89], v[50:51], v[56:57], v[88:89] op_sel:[0,0,0] op_sel_hi:[0,1,1]
	v_pk_fma_f32 v[90:91], v[50:51], v[56:57], v[90:91] op_sel:[1,0,0] op_sel_hi:[1,1,1]
	v_cndmask_b32_e64 v33, v33, v28, s[6:7]
	v_pk_fma_f32 v[2:3], v[44:45], v[22:23], v[84:85] op_sel:[0,0,0] op_sel_hi:[0,1,1] neg_lo:[1,0,0] neg_hi:[1,0,0]
	v_pk_fma_f32 v[4:5], v[44:45], v[22:23], v[86:87] op_sel:[1,0,0] op_sel_hi:[1,1,1] neg_lo:[1,0,0] neg_hi:[1,0,0]
	v_pk_fma_f32 v[6:7], v[46:47], v[22:23], v[88:89] op_sel:[0,0,0] op_sel_hi:[0,1,1] neg_lo:[1,0,0] neg_hi:[1,0,0]
	v_pk_fma_f32 v[8:9], v[46:47], v[22:23], v[90:91] op_sel:[1,0,0] op_sel_hi:[1,1,1] neg_lo:[1,0,0] neg_hi:[1,0,0]
	s_waitcnt lgkmcnt(0)
	v_pk_mul_f32 v[22:23], v[2:3], v[60:61] op_sel:[0,0] op_sel_hi:[1,0]
	v_pk_mul_f32 v[28:29], v[2:3], v[52:53] op_sel:[0,0] op_sel_hi:[1,0]
	v_pk_fma_f32 v[22:23], v[4:5], v[60:61], v[22:23] op_sel:[0,1,0] op_sel_hi:[1,1,1]
	v_pk_fma_f32 v[28:29], v[4:5], v[52:53], v[28:29] op_sel:[0,1,0] op_sel_hi:[1,1,1]
	v_pk_fma_f32 v[22:23], v[6:7], v[62:63], v[22:23] op_sel:[0,0,0] op_sel_hi:[1,0,1]
	v_pk_fma_f32 v[28:29], v[6:7], v[54:55], v[28:29] op_sel:[0,0,0] op_sel_hi:[1,0,1]
	v_pk_fma_f32 v[22:23], v[8:9], v[62:63], v[22:23] op_sel:[0,1,0] op_sel_hi:[1,1,1]
	v_pk_fma_f32 v[28:29], v[8:9], v[54:55], v[28:29] op_sel:[0,1,0] op_sel_hi:[1,1,1]
	v_add_f32_dpp v24, v24, v24 row_ror:12 row_mask:0xf bank_mask:0x5
	v_add_f32_dpp v25, v25, v25 row_ror:4 row_mask:0xf bank_mask:0xa
	v_add_f32_dpp v22, v22, v22 quad_perm:[1,0,3,2] row_mask:0xf bank_mask:0xf
	v_add_f32_dpp v23, v23, v23 quad_perm:[1,0,3,2] row_mask:0xf bank_mask:0xf
	v_pk_mul_f32 v[84:85], v[2:3], v[64:65] op_sel:[0,0] op_sel_hi:[1,0]
	v_pk_mul_f32 v[86:87], v[4:5], v[64:65] op_sel:[0,1] op_sel_hi:[1,1]
	v_add_f32_dpp v26, v26, v26 row_ror:12 row_mask:0xf bank_mask:0x5
	v_add_f32_dpp v22, v22, v22 quad_perm:[2,3,0,1] row_mask:0xf bank_mask:0xf
	v_add_f32_dpp v23, v23, v23 quad_perm:[2,3,0,1] row_mask:0xf bank_mask:0xf
	v_pk_mul_f32 v[88:89], v[6:7], v[66:67] op_sel:[0,0] op_sel_hi:[1,0]
	v_pk_mul_f32 v[90:91], v[8:9], v[66:67] op_sel:[0,1] op_sel_hi:[1,1]
	v_add_f32_dpp v27, v27, v27 row_ror:4 row_mask:0xf bank_mask:0xa
	v_add_f32_dpp v22, v22, v22 row_half_mirror row_mask:0xf bank_mask:0xf
	v_add_f32_dpp v23, v23, v23 row_half_mirror row_mask:0xf bank_mask:0xf
	v_pk_fma_f32 v[84:85], v[72:73], v[80:81], v[84:85] op_sel:[0,0,0] op_sel_hi:[0,1,1]
	v_pk_fma_f32 v[86:87], v[72:73], v[80:81], v[86:87] op_sel:[1,0,0] op_sel_hi:[1,1,1]
	v_mov_b32_dpp v24, v25 quad_perm:[0,1,2,3] row_mask:0xf bank_mask:0xa
	v_add_f32_dpp v22, v22, v22 row_mirror row_mask:0xf bank_mask:0xf
	v_add_f32_dpp v23, v23, v23 row_mirror row_mask:0xf bank_mask:0xf
	v_pk_fma_f32 v[88:89], v[74:75], v[80:81], v[88:89] op_sel:[0,0,0] op_sel_hi:[0,1,1]
	v_pk_fma_f32 v[90:91], v[74:75], v[80:81], v[90:91] op_sel:[1,0,0] op_sel_hi:[1,1,1]
	v_mov_b32_dpp v26, v27 quad_perm:[0,1,2,3] row_mask:0xf bank_mask:0xa
	v_pk_fma_f32 v[2:3], v[68:69], v[22:23], v[84:85] op_sel:[0,0,0] op_sel_hi:[0,1,1] neg_lo:[1,0,0] neg_hi:[1,0,0]
	v_pk_fma_f32 v[4:5], v[68:69], v[22:23], v[86:87] op_sel:[1,0,0] op_sel_hi:[1,1,1] neg_lo:[1,0,0] neg_hi:[1,0,0]
	v_pk_fma_f32 v[6:7], v[70:71], v[22:23], v[88:89] op_sel:[0,0,0] op_sel_hi:[0,1,1] neg_lo:[1,0,0] neg_hi:[1,0,0]
	v_pk_fma_f32 v[8:9], v[70:71], v[22:23], v[90:91] op_sel:[1,0,0] op_sel_hi:[1,1,1] neg_lo:[1,0,0] neg_hi:[1,0,0]
	s_waitcnt lgkmcnt(0)
	v_pk_mul_f32 v[58:59], v[2:3], v[76:77] op_sel:[0,0] op_sel_hi:[1,0]
	v_pk_fma_f32 v[58:59], v[4:5], v[76:77], v[58:59] op_sel:[0,1,0] op_sel_hi:[1,1,1]
	v_pk_fma_f32 v[58:59], v[6:7], v[78:79], v[58:59] op_sel:[0,0,0] op_sel_hi:[1,0,1]
	v_pk_fma_f32 v[58:59], v[8:9], v[78:79], v[58:59] op_sel:[0,1,0] op_sel_hi:[1,1,1]
	v_add_f32_dpp v28, v28, v28 row_ror:12 row_mask:0xf bank_mask:0x5
	v_add_f32_dpp v29, v29, v29 row_ror:4 row_mask:0xf bank_mask:0xa
	v_add_f32_dpp v24, v24, v24 row_ror:8 row_mask:0xf bank_mask:0x3
	v_add_f32_dpp v26, v26, v26 row_ror:8 row_mask:0xf bank_mask:0xc
	v_add_f32_dpp v58, v58, v58 row_ror:12 row_mask:0xf bank_mask:0x5
	v_add_f32_dpp v59, v59, v59 row_ror:4 row_mask:0xf bank_mask:0xa
	v_mov_b32_dpp v24, v26 quad_perm:[0,1,2,3] row_mask:0xf bank_mask:0xc
	v_mov_b32_dpp v28, v29 quad_perm:[0,1,2,3] row_mask:0xf bank_mask:0xa
	v_mov_b32_dpp v58, v59 quad_perm:[0,1,2,3] row_mask:0xf bank_mask:0xa
	v_add_f32_dpp v24, v24, v24 quad_perm:[1,0,3,2] row_mask:0xf bank_mask:0xf
	v_add_f32_dpp v28, v28, v28 row_ror:8 row_mask:0xf bank_mask:0x3
	v_add_f32_dpp v58, v58, v58 row_ror:8 row_mask:0xf bank_mask:0xc
	v_add_f32_dpp v24, v24, v24 quad_perm:[2,3,0,1] row_mask:0xf bank_mask:0xf
	s_nop 0
	v_mov_b32_dpp v28, v58 quad_perm:[0,1,2,3] row_mask:0xf bank_mask:0xc
	v_cndmask_b32_e64 v33, v33, v24, s[8:9]
	s_nop 0
	v_add_f32_dpp v28, v28, v28 quad_perm:[1,0,3,2] row_mask:0xf bank_mask:0xf
	s_nop 1
	v_add_f32_dpp v28, v28, v28 quad_perm:[2,3,0,1] row_mask:0xf bank_mask:0xf
	v_cndmask_b32_e64 v33, v33, v28, s[10:11]
	v_lshl_add_u32 v35, s23, 12, v11
	s_add_i32 s22, s22, 1
	ds_write2st64_b32 v35, v30, v31 offset1:4
	ds_write2st64_b32 v35, v32, v33 offset0:8 offset1:12
	s_cmp_eq_u32 s22, 64
	s_waitcnt lgkmcnt(0)
	s_barrier
	s_cbranch_scc0 .LBB0_1750
	s_setprio 0
	s_lshl_b32 s0, s18, 4
	s_or_b32 s0, s0, s26
	s_ashr_i32 s1, s0, 31
	s_lshl_b64 s[0:1], s[0:1], 6
	s_lshl_b32 s2, s27, 5
	s_or_b32 s0, s0, s2
	v_or_b32_e32 v12, s0, v1
	v_mov_b32_e32 v13, s1
	v_lshlrev_b64 v[12:13], 8, v[12:13]
	v_lshl_add_u64 v[12:13], s[82:83], 0, v[12:13]
	v_mov_b32_e32 v11, 0
	v_lshl_add_u64 v[10:11], v[12:13], 0, v[10:11]
	s_mov_b64 s[0:1], 0x4100000
	v_lshl_add_u64 v[12:13], v[10:11], 0, s[0:1]
	v_add_co_u32_e32 v10, vcc, 0x4100000, v10
	s_nop 1
	v_addc_co_u32_e32 v11, vcc, 0, v11, vcc
	v_mov_b32_e32 v14, v2
	v_mov_b32_e32 v15, v4
	v_mov_b32_e32 v16, v6
	v_mov_b32_e32 v17, v8
	v_mov_b32_e32 v18, v3
	v_mov_b32_e32 v19, v5
	v_mov_b32_e32 v20, v7
	v_mov_b32_e32 v21, v9
	global_store_dwordx4 v[10:11], v[14:17], off
	global_store_dwordx4 v[12:13], v[18:21], off offset:256
